# GEMM mainloops: remaining +128 DMA sites use a scalar base built in s[100:101]; 11 dead 64-bit address adds removed
# baseline (speedup 1.0000x reference)
; #define PG8_STAGE(bufoff, gbase, voff) do { _Pragma("unroll") for (int _i = 0; _i < 2; ++_i) \
;         __builtin_amdgcn_global_load_lds((const unsigned*)((const char*)(gbase) + (voff)[_i]), (LAS unsigned*)(lds + (bufoff) + ldsw + _i * 8192), 16, 0, 0); } while (0)
; #define PG8_LDA(dst, b, h) do { _Pragma("unroll") for (int m = 0; m < 4; ++m) _Pragma("unroll") for (int k = 0; k < 2; ++k) dst[m][k] = *(const LAS bf16x8*)(lds + PG8_SA(b, h) + aoff + m * 2048 + k * 1024); } while (0)
; #define PG8_LDB(dst, b, h) do { _Pragma("unroll") for (int n = 0; n < 2; ++n) _Pragma("unroll") for (int k = 0; k < 2; ++k) dst[n][k] = *(const LAS bf16x8*)(lds + PG8_SB(b, h) + boff + n * 2048 + k * 1024); } while (0)
; #define PG8_MMA(ai, bj, At, Bt) do { __builtin_amdgcn_s_setprio(1); _Pragma("unroll") for (int m = 0; m < 4; ++m) _Pragma("unroll") for (int n = 0; n < 2; ++n) _Pragma("unroll") for (int k = 0; k < 2; ++k) \
;         acc[ai][bj][m][n] = __builtin_amdgcn_mfma_f32_16x16x32_bf16(Bt[n][k], At[m][k], acc[ai][bj][m][n], 0, 0, 0); __builtin_amdgcn_s_setprio(0); } while (0)
; #define PG8_BAR __builtin_amdgcn_s_barrier()
; template <class Epi>
; __device__ __forceinline__ void gemm_phase(LAS unsigned char* lds, const Gemm g, const StaticOrder& S, const Epi& E, const int tid) {
;     ...
;         const char* nA = has_next ? (const char*)g.A + (size_t)nxt.pm * tstepA : cA; const char* nB = has_next ? (const char*)g.Bt + (size_t)nxt.pn * tstepB : cB;
;         for (int t = 0; t < nt; t += 2) {
;             const bool last = (t == nt - 2);
;             const char* a1 = cA + (size_t)(t + 1) * kstep + ((t + 1) >= 8 ? xtra : 0);
;             const char* a2 = last ? nA : cA + (size_t)(t + 2) * kstep + ((t + 2) >= 8 ? xtra : 0); const char* b2 = last ? nB : cB + (size_t)(t + 2) * kstep;
;             const char* a3 = a2 + kstep; const char* b3 = b2 + kstep;
;             PG8_LDB(B0, 0, 0); PG8_LDB(B1, 0, 1); PG8_SCHED; PG8_LDA(At, 0, 0); PG8_STAGE(PG8_SA(1, 1), a1 + hstepA, voffA);
;             PG8_WAIT_V(8); PG8_WAIT_L(0); PG8_BAR; PG8_MMA(0, 0, At, B0); PG8_MMA(0, 1, At, B1); PG8_BAR; PG8_SCHED;
;             PG8_LDA(At, 0, 1); PG8_STAGE(PG8_SB(0, 0), b2, voffB); PG8_STAGE(PG8_SB(0, 1), b2 + hstepB, voffB); PG8_STAGE(PG8_SA(0, 0), a2, voffA);
;             PG8_WAIT_V(8); PG8_WAIT_L(0); PG8_BAR; PG8_MMA(1, 0, At, B0); PG8_MMA(1, 1, At, B1); PG8_BAR; PG8_SCHED;
.LBB0_160:
	s_add_u32 s42, s94, 0x100
	s_addc_u32 s43, s95, 0
	s_add_i32 s8, 0, 0x10000
	v_add_u32_e32 v142, s8, v245
	v_add_u32_e32 v158, s15, v245
	ds_read_b128 v[122:125], v142
	ds_read_b128 v[126:129], v142 offset:1024
	ds_read_b128 v[138:141], v142 offset:2048
	ds_read_b128 v[142:145], v142 offset:3072
	ds_read_b128 v[146:149], v158
	ds_read_b128 v[150:153], v158 offset:1024
	ds_read_b128 v[154:157], v158 offset:2048
	ds_read_b128 v[158:161], v158 offset:3072
	s_cmp_eq_u32 s89, 12
	s_cselect_b32 vcc_hi, s91, s43
	s_cselect_b32 vcc_lo, s90, s42
	s_cselect_b32 s93, s36, s46
	s_cselect_b32 s92, s37, s45
	v_lshl_add_u64 v[210:211], s[94:95], 0, v[206:207]
	s_add_i32 m0, s19, 0xc000
	ds_read_b128 v[162:165], v246
	ds_read_b128 v[166:169], v246 offset:1024
	ds_read_b128 v[170:173], v246 offset:2048
	ds_read_b128 v[174:177], v246 offset:3072
	ds_read_b128 v[178:181], v246 offset:4096
	ds_read_b128 v[182:185], v246 offset:5120
	ds_read_b128 v[186:189], v246 offset:6144
	ds_read_b128 v[190:193], v246 offset:7168
	global_load_lds_dwordx4 v[210:211], off
	v_lshl_add_u64 v[210:211], s[94:95], 0, v[208:209]
	s_add_i32 m0, s19, 0xe000
	s_nop 0
	global_load_lds_dwordx4 v[210:211], off
	s_waitcnt vmcnt(8)
	s_waitcnt lgkmcnt(0)
	s_barrier
	s_setprio 1
	s_waitcnt lgkmcnt(0)
	v_mfma_f32_16x16x32_bf16 v[134:137], v[122:125], v[162:165], v[134:137]
	v_mfma_f32_16x16x32_bf16 v[130:133], v[138:141], v[162:165], v[130:133]
	v_mfma_f32_16x16x32_bf16 v[108:111], v[122:125], v[170:173], v[108:111]
	v_mfma_f32_16x16x32_bf16 v[104:107], v[138:141], v[170:173], v[104:107]
	v_mfma_f32_16x16x32_bf16 v[92:95], v[122:125], v[178:181], v[92:95]
	v_mfma_f32_16x16x32_bf16 v[88:91], v[138:141], v[178:181], v[88:91]
	v_mfma_f32_16x16x32_bf16 v[76:79], v[122:125], v[186:189], v[76:79]
	v_mfma_f32_16x16x32_bf16 v[72:75], v[138:141], v[186:189], v[72:75]
	v_mfma_f32_16x16x32_bf16 v[134:137], v[126:129], v[166:169], v[134:137]
	v_mfma_f32_16x16x32_bf16 v[130:133], v[142:145], v[166:169], v[130:133]
	v_mfma_f32_16x16x32_bf16 v[108:111], v[126:129], v[174:177], v[108:111]
	v_mfma_f32_16x16x32_bf16 v[104:107], v[142:145], v[174:177], v[104:107]
	v_mfma_f32_16x16x32_bf16 v[92:95], v[126:129], v[182:185], v[92:95]
	v_mfma_f32_16x16x32_bf16 v[88:91], v[142:145], v[182:185], v[88:91]
	v_mfma_f32_16x16x32_bf16 v[76:79], v[126:129], v[190:193], v[76:79]
	v_mfma_f32_16x16x32_bf16 v[72:75], v[142:145], v[190:193], v[72:75]
	v_mfma_f32_16x16x32_bf16 v[118:121], v[146:149], v[162:165], v[118:121]
	v_mfma_f32_16x16x32_bf16 v[114:117], v[154:157], v[162:165], v[114:117]
	v_mfma_f32_16x16x32_bf16 v[100:103], v[146:149], v[170:173], v[100:103]
	v_mfma_f32_16x16x32_bf16 v[96:99], v[154:157], v[170:173], v[96:99]
	v_mfma_f32_16x16x32_bf16 v[84:87], v[146:149], v[178:181], v[84:87]
	v_mfma_f32_16x16x32_bf16 v[80:83], v[154:157], v[178:181], v[80:83]
	v_mfma_f32_16x16x32_bf16 v[68:71], v[146:149], v[186:189], v[68:71]
	v_mfma_f32_16x16x32_bf16 v[64:67], v[154:157], v[186:189], v[64:67]
	v_mfma_f32_16x16x32_bf16 v[118:121], v[150:153], v[166:169], v[118:121]
	v_mfma_f32_16x16x32_bf16 v[114:117], v[158:161], v[166:169], v[114:117]
	v_mfma_f32_16x16x32_bf16 v[100:103], v[150:153], v[174:177], v[100:103]
	v_mfma_f32_16x16x32_bf16 v[96:99], v[158:161], v[174:177], v[96:99]
	v_mfma_f32_16x16x32_bf16 v[84:87], v[150:153], v[182:185], v[84:87]
	v_mfma_f32_16x16x32_bf16 v[80:83], v[158:161], v[182:185], v[80:83]
	v_mfma_f32_16x16x32_bf16 v[68:71], v[150:153], v[190:193], v[68:71]
	v_mfma_f32_16x16x32_bf16 v[64:67], v[158:161], v[190:193], v[64:67]
	s_setprio 0
	s_barrier
	s_add_i32 s8, s8, s11
	v_lshl_add_u64 v[210:211], s[92:93], 0, v[112:113]
	s_mov_b32 m0, s8
	ds_read_b128 v[162:165], v246 offset:16384
	ds_read_b128 v[166:169], v246 offset:17408
	ds_read_b128 v[170:173], v246 offset:18432
	ds_read_b128 v[174:177], v246 offset:19456
	ds_read_b128 v[178:181], v246 offset:20480
	ds_read_b128 v[182:185], v246 offset:21504
	ds_read_b128 v[186:189], v246 offset:22528
	ds_read_b128 v[190:193], v246 offset:23552
	global_load_lds_dwordx4 v112, s[92:93]
	s_add_i32 m0, s8, 0x2000
	s_add_u32 s8, s92, 0x40000
	v_lshl_add_u64 v[212:213], s[92:93], 0, v[200:201]
	s_addc_u32 s9, s93, 0
	s_add_i32 s13, s15, s11
	global_load_lds_dwordx4 v200, s[92:93]
	s_nop 0
	s_mov_b32 m0, s13
	s_nop 0
	global_load_lds_dwordx4 v112, s[8:9]
	s_nop 0
	s_add_i32 m0, s13, 0x2000
	s_nop 0
	global_load_lds_dwordx4 v200, s[8:9]
	s_nop 0
	s_mov_b32 m0, s19
	s_nop 0
	global_load_lds_dwordx4 v202, vcc
	s_mov_b32 m0, s28
	s_nop 0
	global_load_lds_dwordx4 v204, vcc
	s_waitcnt vmcnt(8)
	s_waitcnt lgkmcnt(0)
	s_barrier
; #define PG8_STAGE(bufoff, gbase, voff) do { _Pragma("unroll") for (int _i = 0; _i < 2; ++_i) \
;         __builtin_amdgcn_global_load_lds((const unsigned*)((const char*)(gbase) + (voff)[_i]), (LAS unsigned*)(lds + (bufoff) + ldsw + _i * 8192), 16, 0, 0); } while (0)
; #define PG8_LDA(dst, b, h) do { _Pragma("unroll") for (int m = 0; m < 4; ++m) _Pragma("unroll") for (int k = 0; k < 2; ++k) dst[m][k] = *(const LAS bf16x8*)(lds + PG8_SA(b, h) + aoff + m * 2048 + k * 1024); } while (0)
; #define PG8_LDB(dst, b, h) do { _Pragma("unroll") for (int n = 0; n < 2; ++n) _Pragma("unroll") for (int k = 0; k < 2; ++k) dst[n][k] = *(const LAS bf16x8*)(lds + PG8_SB(b, h) + boff + n * 2048 + k * 1024); } while (0)
; #define PG8_MMA(ai, bj, At, Bt) do { __builtin_amdgcn_s_setprio(1); _Pragma("unroll") for (int m = 0; m < 4; ++m) _Pragma("unroll") for (int n = 0; n < 2; ++n) _Pragma("unroll") for (int k = 0; k < 2; ++k) \
;         acc[ai][bj][m][n] = __builtin_amdgcn_mfma_f32_16x16x32_bf16(Bt[n][k], At[m][k], acc[ai][bj][m][n], 0, 0, 0); __builtin_amdgcn_s_setprio(0); } while (0)
; #define PG8_WAIT_V(n) asm volatile("s_waitcnt vmcnt(" #n ")" ::: "memory")
; #define PG8_WAIT_L(n) asm volatile("s_waitcnt lgkmcnt(" #n ")" ::: "memory")
; #define PG8_BAR __builtin_amdgcn_s_barrier()
; #define PG8_SCHED __builtin_amdgcn_sched_barrier(0)
; template <class Epi>
; __device__ __forceinline__ void gemm_phase(LAS unsigned char* lds, const Gemm g, const StaticOrder& S, const Epi& E, const int tid) {
;     ...
;             PG8_WAIT_V(8); PG8_WAIT_L(0); PG8_BAR; PG8_MMA(1, 0, At, B0); PG8_MMA(1, 1, At, B1); PG8_BAR; PG8_SCHED;
;             PG8_LDB(B0, 1, 0); PG8_LDB(B1, 1, 1); PG8_SCHED; PG8_LDA(At, 1, 0); PG8_STAGE(PG8_SA(0, 1), a2 + hstepA, voffA);
;             PG8_WAIT_V(8); PG8_WAIT_L(0); PG8_BAR; PG8_MMA(0, 0, At, B0); PG8_MMA(0, 1, At, B1); PG8_BAR; PG8_SCHED;
	s_setprio 1
	s_waitcnt lgkmcnt(0)
	v_mfma_f32_16x16x32_bf16 v[60:63], v[122:125], v[162:165], v[60:63]
	v_mfma_f32_16x16x32_bf16 v[56:59], v[138:141], v[162:165], v[56:59]
	v_mfma_f32_16x16x32_bf16 v[44:47], v[122:125], v[170:173], v[44:47]
	v_mfma_f32_16x16x32_bf16 v[40:43], v[138:141], v[170:173], v[40:43]
	v_mfma_f32_16x16x32_bf16 v[28:31], v[122:125], v[178:181], v[28:31]
	v_mfma_f32_16x16x32_bf16 v[24:27], v[138:141], v[178:181], v[24:27]
	v_mfma_f32_16x16x32_bf16 v[12:15], v[122:125], v[186:189], v[12:15]
	v_mfma_f32_16x16x32_bf16 v[8:11], v[138:141], v[186:189], v[8:11]
	v_mfma_f32_16x16x32_bf16 v[60:63], v[126:129], v[166:169], v[60:63]
	v_mfma_f32_16x16x32_bf16 v[56:59], v[142:145], v[166:169], v[56:59]
	v_mfma_f32_16x16x32_bf16 v[44:47], v[126:129], v[174:177], v[44:47]
	v_mfma_f32_16x16x32_bf16 v[40:43], v[142:145], v[174:177], v[40:43]
	v_mfma_f32_16x16x32_bf16 v[28:31], v[126:129], v[182:185], v[28:31]
	v_mfma_f32_16x16x32_bf16 v[24:27], v[142:145], v[182:185], v[24:27]
	v_mfma_f32_16x16x32_bf16 v[12:15], v[126:129], v[190:193], v[12:15]
	v_mfma_f32_16x16x32_bf16 v[8:11], v[142:145], v[190:193], v[8:11]
	v_mfma_f32_16x16x32_bf16 v[52:55], v[146:149], v[162:165], v[52:55]
	v_mfma_f32_16x16x32_bf16 v[48:51], v[154:157], v[162:165], v[48:51]
	v_mfma_f32_16x16x32_bf16 v[36:39], v[146:149], v[170:173], v[36:39]
	v_mfma_f32_16x16x32_bf16 v[32:35], v[154:157], v[170:173], v[32:35]
	v_mfma_f32_16x16x32_bf16 v[20:23], v[146:149], v[178:181], v[20:23]
	v_mfma_f32_16x16x32_bf16 v[16:19], v[154:157], v[178:181], v[16:19]
	v_mfma_f32_16x16x32_bf16 v[4:7], v[146:149], v[186:189], v[4:7]
	v_mfma_f32_16x16x32_bf16 v[0:3], v[154:157], v[186:189], v[0:3]
	v_mfma_f32_16x16x32_bf16 v[52:55], v[150:153], v[166:169], v[52:55]
	v_mfma_f32_16x16x32_bf16 v[48:51], v[158:161], v[166:169], v[48:51]
	v_mfma_f32_16x16x32_bf16 v[36:39], v[150:153], v[174:177], v[36:39]
	v_mfma_f32_16x16x32_bf16 v[32:35], v[158:161], v[174:177], v[32:35]
	v_mfma_f32_16x16x32_bf16 v[20:23], v[150:153], v[182:185], v[20:23]
	v_mfma_f32_16x16x32_bf16 v[16:19], v[158:161], v[182:185], v[16:19]
	v_mfma_f32_16x16x32_bf16 v[4:7], v[150:153], v[190:193], v[4:7]
	v_mfma_f32_16x16x32_bf16 v[0:3], v[158:161], v[190:193], v[0:3]
	s_setprio 0
	s_barrier
	s_add_i32 s13, 0, 0x18000
	s_add_i32 s31, 0, 0x1c000
	v_add_u32_e32 v142, s13, v245
	v_add_u32_e32 v158, s31, v245
	ds_read_b128 v[122:125], v142
	ds_read_b128 v[126:129], v142 offset:1024
	ds_read_b128 v[138:141], v142 offset:2048
	ds_read_b128 v[142:145], v142 offset:3072
	ds_read_b128 v[146:149], v158
	ds_read_b128 v[150:153], v158 offset:1024
	ds_read_b128 v[154:157], v158 offset:2048
	ds_read_b128 v[158:161], v158 offset:3072
	s_add_u32 s8, vcc_lo, 0xc0000
	s_addc_u32 s9, vcc_hi, 0
	s_mov_b32 m0, s30
	s_nop 0
	ds_read_b128 v[162:165], v246 offset:32768
	ds_read_b128 v[166:169], v246 offset:33792
	ds_read_b128 v[170:173], v246 offset:34816
	ds_read_b128 v[174:177], v246 offset:35840
	ds_read_b128 v[178:181], v246 offset:36864
	ds_read_b128 v[182:185], v246 offset:37888
	ds_read_b128 v[186:189], v246 offset:38912
	ds_read_b128 v[190:193], v246 offset:39936
	global_load_lds_dwordx4 v202, s[8:9]
	v_lshl_add_u64 v[248:249], s[8:9], 0, v[204:205]
	s_mov_b32 m0, s35
	s_nop 0
	global_load_lds_dwordx4 v204, s[8:9]
	s_waitcnt vmcnt(8)
	s_waitcnt lgkmcnt(0)
	s_barrier
	s_setprio 1
	s_waitcnt lgkmcnt(0)
	v_mfma_f32_16x16x32_bf16 v[134:137], v[122:125], v[162:165], v[134:137]
	v_mfma_f32_16x16x32_bf16 v[130:133], v[138:141], v[162:165], v[130:133]
	v_mfma_f32_16x16x32_bf16 v[108:111], v[122:125], v[170:173], v[108:111]
	v_mfma_f32_16x16x32_bf16 v[104:107], v[138:141], v[170:173], v[104:107]
	v_mfma_f32_16x16x32_bf16 v[92:95], v[122:125], v[178:181], v[92:95]
	v_mfma_f32_16x16x32_bf16 v[88:91], v[138:141], v[178:181], v[88:91]
	v_mfma_f32_16x16x32_bf16 v[76:79], v[122:125], v[186:189], v[76:79]
	v_mfma_f32_16x16x32_bf16 v[72:75], v[138:141], v[186:189], v[72:75]
	v_mfma_f32_16x16x32_bf16 v[134:137], v[126:129], v[166:169], v[134:137]
	v_mfma_f32_16x16x32_bf16 v[130:133], v[142:145], v[166:169], v[130:133]
	v_mfma_f32_16x16x32_bf16 v[108:111], v[126:129], v[174:177], v[108:111]
	v_mfma_f32_16x16x32_bf16 v[104:107], v[142:145], v[174:177], v[104:107]
	v_mfma_f32_16x16x32_bf16 v[92:95], v[126:129], v[182:185], v[92:95]
	v_mfma_f32_16x16x32_bf16 v[88:91], v[142:145], v[182:185], v[88:91]
	v_mfma_f32_16x16x32_bf16 v[76:79], v[126:129], v[190:193], v[76:79]
	v_mfma_f32_16x16x32_bf16 v[72:75], v[142:145], v[190:193], v[72:75]
	v_mfma_f32_16x16x32_bf16 v[118:121], v[146:149], v[162:165], v[118:121]
	v_mfma_f32_16x16x32_bf16 v[114:117], v[154:157], v[162:165], v[114:117]
	v_mfma_f32_16x16x32_bf16 v[100:103], v[146:149], v[170:173], v[100:103]
	v_mfma_f32_16x16x32_bf16 v[96:99], v[154:157], v[170:173], v[96:99]
	v_mfma_f32_16x16x32_bf16 v[84:87], v[146:149], v[178:181], v[84:87]
	v_mfma_f32_16x16x32_bf16 v[80:83], v[154:157], v[178:181], v[80:83]
	v_mfma_f32_16x16x32_bf16 v[68:71], v[146:149], v[186:189], v[68:71]
	v_mfma_f32_16x16x32_bf16 v[64:67], v[154:157], v[186:189], v[64:67]
	v_mfma_f32_16x16x32_bf16 v[118:121], v[150:153], v[166:169], v[118:121]
	v_mfma_f32_16x16x32_bf16 v[114:117], v[158:161], v[166:169], v[114:117]
	v_mfma_f32_16x16x32_bf16 v[100:103], v[150:153], v[174:177], v[100:103]
	v_mfma_f32_16x16x32_bf16 v[96:99], v[158:161], v[174:177], v[96:99]
	v_mfma_f32_16x16x32_bf16 v[84:87], v[150:153], v[182:185], v[84:87]
	v_mfma_f32_16x16x32_bf16 v[80:83], v[158:161], v[182:185], v[80:83]
	v_mfma_f32_16x16x32_bf16 v[68:71], v[150:153], v[190:193], v[68:71]
	v_mfma_f32_16x16x32_bf16 v[64:67], v[158:161], v[190:193], v[64:67]
	s_setprio 0
	s_barrier
; #define PG8_STAGE(bufoff, gbase, voff) do { _Pragma("unroll") for (int _i = 0; _i < 2; ++_i) \
;         __builtin_amdgcn_global_load_lds((const unsigned*)((const char*)(gbase) + (voff)[_i]), (LAS unsigned*)(lds + (bufoff) + ldsw + _i * 8192), 16, 0, 0); } while (0)
; #define PG8_LDA(dst, b, h) do { _Pragma("unroll") for (int m = 0; m < 4; ++m) _Pragma("unroll") for (int k = 0; k < 2; ++k) dst[m][k] = *(const LAS bf16x8*)(lds + PG8_SA(b, h) + aoff + m * 2048 + k * 1024); } while (0)
; #define PG8_MMA(ai, bj, At, Bt) do { __builtin_amdgcn_s_setprio(1); _Pragma("unroll") for (int m = 0; m < 4; ++m) _Pragma("unroll") for (int n = 0; n < 2; ++n) _Pragma("unroll") for (int k = 0; k < 2; ++k) \
;         acc[ai][bj][m][n] = __builtin_amdgcn_mfma_f32_16x16x32_bf16(Bt[n][k], At[m][k], acc[ai][bj][m][n], 0, 0, 0); __builtin_amdgcn_s_setprio(0); } while (0)
; #define PG8_WAIT_V(n) asm volatile("s_waitcnt vmcnt(" #n ")" ::: "memory")
; #define PG8_WAIT_L(n) asm volatile("s_waitcnt lgkmcnt(" #n ")" ::: "memory")
; #define PG8_BAR __builtin_amdgcn_s_barrier()
; #define PG8_SCHED __builtin_amdgcn_sched_barrier(0)
; template <class Epi>
; __device__ __forceinline__ void gemm_phase(LAS unsigned char* lds, const Gemm g, const StaticOrder& S, const Epi& E, const int tid) {
;     ...
;             PG8_LDA(At, 1, 1); PG8_STAGE(PG8_SB(1, 0), b3, voffB); PG8_STAGE(PG8_SB(1, 1), b3 + hstepB, voffB); PG8_STAGE(PG8_SA(1, 0), a3, voffA);
;             PG8_WAIT_V(8); PG8_WAIT_L(0); PG8_BAR; PG8_MMA(1, 0, At, B0); PG8_MMA(1, 1, At, B1); PG8_BAR; PG8_SCHED;
;         }
;         if (wr == 0) PG8_BAR;
	s_add_i32 s8, s13, s11
	s_add_u32 s100, s92, 0x80
	s_addc_u32 s101, s93, 0
	s_mov_b32 m0, s8
	ds_read_b128 v[162:165], v246 offset:49152
	ds_read_b128 v[166:169], v246 offset:50176
	ds_read_b128 v[170:173], v246 offset:51200
	ds_read_b128 v[174:177], v246 offset:52224
	ds_read_b128 v[178:181], v246 offset:53248
	ds_read_b128 v[182:185], v246 offset:54272
	ds_read_b128 v[186:189], v246 offset:55296
	ds_read_b128 v[190:193], v246 offset:56320
	global_load_lds_dwordx4 v112, s[100:101]
	s_add_i32 m0, s8, 0x2000
	s_add_u32 s8, s92, 0x40080
	v_lshl_add_u64 v[210:211], v[212:213], 0, s[24:25]
	s_addc_u32 s9, s93, 0
	s_add_i32 s13, s31, s11
	global_load_lds_dwordx4 v[210:211], off
	s_nop 0
	s_mov_b32 m0, s13
	s_nop 0
	global_load_lds_dwordx4 v112, s[8:9]
	s_nop 0
	s_add_i32 m0, s13, 0x2000
	s_nop 0
	global_load_lds_dwordx4 v200, s[8:9]
	s_add_u32 s100, vcc_lo, 0x80
	s_addc_u32 s101, vcc_hi, 0
	s_mov_b32 m0, s38
	s_nop 0
	global_load_lds_dwordx4 v202, s[100:101]
	s_add_u32 s100, vcc_lo, 0x80
	s_addc_u32 s101, vcc_hi, 0
	s_mov_b32 m0, s39
	s_nop 0
	global_load_lds_dwordx4 v204, s[100:101]
	s_waitcnt vmcnt(8)
	s_waitcnt lgkmcnt(0)
	s_barrier
	s_setprio 1
	s_waitcnt lgkmcnt(0)
	v_mfma_f32_16x16x32_bf16 v[60:63], v[122:125], v[162:165], v[60:63]
	v_mfma_f32_16x16x32_bf16 v[56:59], v[138:141], v[162:165], v[56:59]
	v_mfma_f32_16x16x32_bf16 v[44:47], v[122:125], v[170:173], v[44:47]
	v_mfma_f32_16x16x32_bf16 v[40:43], v[138:141], v[170:173], v[40:43]
	v_mfma_f32_16x16x32_bf16 v[28:31], v[122:125], v[178:181], v[28:31]
	v_mfma_f32_16x16x32_bf16 v[24:27], v[138:141], v[178:181], v[24:27]
	v_mfma_f32_16x16x32_bf16 v[12:15], v[122:125], v[186:189], v[12:15]
	v_mfma_f32_16x16x32_bf16 v[8:11], v[138:141], v[186:189], v[8:11]
	v_mfma_f32_16x16x32_bf16 v[60:63], v[126:129], v[166:169], v[60:63]
	v_mfma_f32_16x16x32_bf16 v[56:59], v[142:145], v[166:169], v[56:59]
	v_mfma_f32_16x16x32_bf16 v[44:47], v[126:129], v[174:177], v[44:47]
	v_mfma_f32_16x16x32_bf16 v[40:43], v[142:145], v[174:177], v[40:43]
	v_mfma_f32_16x16x32_bf16 v[28:31], v[126:129], v[182:185], v[28:31]
	v_mfma_f32_16x16x32_bf16 v[24:27], v[142:145], v[182:185], v[24:27]
	v_mfma_f32_16x16x32_bf16 v[12:15], v[126:129], v[190:193], v[12:15]
	v_mfma_f32_16x16x32_bf16 v[8:11], v[142:145], v[190:193], v[8:11]
	v_mfma_f32_16x16x32_bf16 v[52:55], v[146:149], v[162:165], v[52:55]
	v_mfma_f32_16x16x32_bf16 v[48:51], v[154:157], v[162:165], v[48:51]
	v_mfma_f32_16x16x32_bf16 v[36:39], v[146:149], v[170:173], v[36:39]
	v_mfma_f32_16x16x32_bf16 v[32:35], v[154:157], v[170:173], v[32:35]
	v_mfma_f32_16x16x32_bf16 v[20:23], v[146:149], v[178:181], v[20:23]
	v_mfma_f32_16x16x32_bf16 v[16:19], v[154:157], v[178:181], v[16:19]
	v_mfma_f32_16x16x32_bf16 v[4:7], v[146:149], v[186:189], v[4:7]
	v_mfma_f32_16x16x32_bf16 v[0:3], v[154:157], v[186:189], v[0:3]
	v_mfma_f32_16x16x32_bf16 v[52:55], v[150:153], v[166:169], v[52:55]
	v_mfma_f32_16x16x32_bf16 v[48:51], v[158:161], v[166:169], v[48:51]
	v_mfma_f32_16x16x32_bf16 v[36:39], v[150:153], v[174:177], v[36:39]
	v_mfma_f32_16x16x32_bf16 v[32:35], v[158:161], v[174:177], v[32:35]
	v_mfma_f32_16x16x32_bf16 v[20:23], v[150:153], v[182:185], v[20:23]
	v_mfma_f32_16x16x32_bf16 v[16:19], v[158:161], v[182:185], v[16:19]
	v_mfma_f32_16x16x32_bf16 v[4:7], v[150:153], v[190:193], v[4:7]
	v_mfma_f32_16x16x32_bf16 v[0:3], v[158:161], v[190:193], v[0:3]
	s_setprio 0
	s_barrier
	s_add_i32 s89, s89, 2
	s_add_u32 s45, s45, 0x100
	s_addc_u32 s46, s46, 0
	s_cmp_gt_u32 s89, 13
	s_mov_b64 s[94:95], s[42:43]
	s_cbranch_scc0 .LBB0_160
	s_and_b64 vcc, exec, s[86:87]
	s_cbranch_vccz .LBB0_163
	s_barrier

; #define PG8_STAGE(bufoff, gbase, voff) do { _Pragma("unroll") for (int _i = 0; _i < 2; ++_i) \
;         __builtin_amdgcn_global_load_lds((const unsigned*)((const char*)(gbase) + (voff)[_i]), (LAS unsigned*)(lds + (bufoff) + ldsw + _i * 8192), 16, 0, 0); } while (0)
; #define PG8_LDA(dst, b, h) do { _Pragma("unroll") for (int m = 0; m < 4; ++m) _Pragma("unroll") for (int k = 0; k < 2; ++k) dst[m][k] = *(const LAS bf16x8*)(lds + PG8_SA(b, h) + aoff + m * 2048 + k * 1024); } while (0)
; #define PG8_LDB(dst, b, h) do { _Pragma("unroll") for (int n = 0; n < 2; ++n) _Pragma("unroll") for (int k = 0; k < 2; ++k) dst[n][k] = *(const LAS bf16x8*)(lds + PG8_SB(b, h) + boff + n * 2048 + k * 1024); } while (0)
; #define PG8_MMA(ai, bj, At, Bt) do { __builtin_amdgcn_s_setprio(1); _Pragma("unroll") for (int m = 0; m < 4; ++m) _Pragma("unroll") for (int n = 0; n < 2; ++n) _Pragma("unroll") for (int k = 0; k < 2; ++k) \
;         acc[ai][bj][m][n] = __builtin_amdgcn_mfma_f32_16x16x32_bf16(Bt[n][k], At[m][k], acc[ai][bj][m][n], 0, 0, 0); __builtin_amdgcn_s_setprio(0); } while (0)
; #define PG8_BAR __builtin_amdgcn_s_barrier()
; template <class Epi>
; __device__ __forceinline__ void gemm_phase(LAS unsigned char* lds, const Gemm g, const StaticOrder& S, const Epi& E, const int tid) {
;     ...
;         const char* nA = has_next ? (const char*)g.A + (size_t)nxt.pm * tstepA : cA; const char* nB = has_next ? (const char*)g.Bt + (size_t)nxt.pn * tstepB : cB;
;         for (int t = 0; t < nt; t += 2) {
;             const bool last = (t == nt - 2);
;             const char* a1 = cA + (size_t)(t + 1) * kstep + ((t + 1) >= 8 ? xtra : 0);
;             const char* a2 = last ? nA : cA + (size_t)(t + 2) * kstep + ((t + 2) >= 8 ? xtra : 0); const char* b2 = last ? nB : cB + (size_t)(t + 2) * kstep;
;             const char* a3 = a2 + kstep; const char* b3 = b2 + kstep;
;             PG8_LDB(B0, 0, 0); PG8_LDB(B1, 0, 1); PG8_SCHED; PG8_LDA(At, 0, 0); PG8_STAGE(PG8_SA(1, 1), a1 + hstepA, voffA);
;             PG8_WAIT_V(8); PG8_WAIT_L(0); PG8_BAR; PG8_MMA(0, 0, At, B0); PG8_MMA(0, 1, At, B1); PG8_BAR; PG8_SCHED;
;             PG8_LDA(At, 0, 1); PG8_STAGE(PG8_SB(0, 0), b2, voffB); PG8_STAGE(PG8_SB(0, 1), b2 + hstepB, voffB); PG8_STAGE(PG8_SA(0, 0), a2, voffA);
;             PG8_WAIT_V(8); PG8_WAIT_L(0); PG8_BAR; PG8_MMA(1, 0, At, B0); PG8_MMA(1, 1, At, B1); PG8_BAR; PG8_SCHED;
.LBB0_230:
	s_add_i32 s96, s40, 2
	s_cmp_gt_u32 s96, 7
	s_cselect_b32 s46, 0x600, 0
	s_cmp_gt_u32 s96, 5
	s_cselect_b32 s8, 0x600, 0
	s_add_u32 s8, s88, s8
	s_addc_u32 s9, s89, 0
	s_add_u32 s8, s8, 0x100
	s_addc_u32 s9, s9, 0
	s_add_i32 s13, 0, 0x10000
	v_add_u32_e32 v142, s13, v210
	v_add_u32_e32 v158, s15, v210
	ds_read_b128 v[130:133], v142
	ds_read_b128 v[134:137], v142 offset:1024
	ds_read_b128 v[138:141], v142 offset:2048
	ds_read_b128 v[142:145], v142 offset:3072
	ds_read_b128 v[146:149], v158
	ds_read_b128 v[150:153], v158 offset:1024
	ds_read_b128 v[154:157], v158 offset:2048
	ds_read_b128 v[158:161], v158 offset:3072
	s_cmp_eq_u32 s40, 12
	s_cselect_b32 s40, s87, vcc_lo
	s_cselect_b32 s91, s83, s9
	s_cselect_b32 s90, s82, s8
	s_cselect_b32 s41, s81, vcc_hi
	v_lshl_add_u64 v[212:213], s[88:89], 0, v[190:191]
	v_lshl_add_u64 v[212:213], v[212:213], 0, s[46:47]
	s_add_i32 m0, s19, 0xc000
	ds_read_b128 v[162:165], v211
	ds_read_b128 v[166:169], v211 offset:1024
	ds_read_b128 v[170:173], v211 offset:2048
	ds_read_b128 v[174:177], v211 offset:3072
	ds_read_b128 v[178:181], v211 offset:4096
	ds_read_b128 v[182:185], v211 offset:5120
	ds_read_b128 v[202:205], v211 offset:6144
	ds_read_b128 v[206:209], v211 offset:7168
	global_load_lds_dwordx4 v[212:213], off
	v_lshl_add_u64 v[212:213], s[88:89], 0, v[192:193]
	v_lshl_add_u64 v[212:213], v[212:213], 0, s[46:47]
	s_add_i32 m0, s19, 0xe000
	s_nop 0
	global_load_lds_dwordx4 v[212:213], off
	s_waitcnt vmcnt(8)
	s_waitcnt lgkmcnt(0)
	s_barrier
	s_setprio 1
	s_waitcnt lgkmcnt(0)
	v_mfma_f32_16x16x32_bf16 v[126:129], v[130:133], v[162:165], v[126:129]
	v_mfma_f32_16x16x32_bf16 v[122:125], v[138:141], v[162:165], v[122:125]
	v_mfma_f32_16x16x32_bf16 v[108:111], v[130:133], v[170:173], v[108:111]
	v_mfma_f32_16x16x32_bf16 v[104:107], v[138:141], v[170:173], v[104:107]
	v_mfma_f32_16x16x32_bf16 v[92:95], v[130:133], v[178:181], v[92:95]
	v_mfma_f32_16x16x32_bf16 v[88:91], v[138:141], v[178:181], v[88:91]
	v_mfma_f32_16x16x32_bf16 v[76:79], v[130:133], v[202:205], v[76:79]
	v_mfma_f32_16x16x32_bf16 v[72:75], v[138:141], v[202:205], v[72:75]
	v_mfma_f32_16x16x32_bf16 v[126:129], v[134:137], v[166:169], v[126:129]
	v_mfma_f32_16x16x32_bf16 v[122:125], v[142:145], v[166:169], v[122:125]
	v_mfma_f32_16x16x32_bf16 v[108:111], v[134:137], v[174:177], v[108:111]
	v_mfma_f32_16x16x32_bf16 v[104:107], v[142:145], v[174:177], v[104:107]
	v_mfma_f32_16x16x32_bf16 v[92:95], v[134:137], v[182:185], v[92:95]
	v_mfma_f32_16x16x32_bf16 v[88:91], v[142:145], v[182:185], v[88:91]
	v_mfma_f32_16x16x32_bf16 v[76:79], v[134:137], v[206:209], v[76:79]
	v_mfma_f32_16x16x32_bf16 v[72:75], v[142:145], v[206:209], v[72:75]
	v_mfma_f32_16x16x32_bf16 v[118:121], v[146:149], v[162:165], v[118:121]
	v_mfma_f32_16x16x32_bf16 v[114:117], v[154:157], v[162:165], v[114:117]
	v_mfma_f32_16x16x32_bf16 v[100:103], v[146:149], v[170:173], v[100:103]
	v_mfma_f32_16x16x32_bf16 v[96:99], v[154:157], v[170:173], v[96:99]
	v_mfma_f32_16x16x32_bf16 v[84:87], v[146:149], v[178:181], v[84:87]
	v_mfma_f32_16x16x32_bf16 v[80:83], v[154:157], v[178:181], v[80:83]
	v_mfma_f32_16x16x32_bf16 v[68:71], v[146:149], v[202:205], v[68:71]
	v_mfma_f32_16x16x32_bf16 v[64:67], v[154:157], v[202:205], v[64:67]
	v_mfma_f32_16x16x32_bf16 v[118:121], v[150:153], v[166:169], v[118:121]
	v_mfma_f32_16x16x32_bf16 v[114:117], v[158:161], v[166:169], v[114:117]
	v_mfma_f32_16x16x32_bf16 v[100:103], v[150:153], v[174:177], v[100:103]
	v_mfma_f32_16x16x32_bf16 v[96:99], v[158:161], v[174:177], v[96:99]
	v_mfma_f32_16x16x32_bf16 v[84:87], v[150:153], v[182:185], v[84:87]
	v_mfma_f32_16x16x32_bf16 v[80:83], v[158:161], v[182:185], v[80:83]
	v_mfma_f32_16x16x32_bf16 v[68:71], v[150:153], v[206:209], v[68:71]
	v_mfma_f32_16x16x32_bf16 v[64:67], v[158:161], v[206:209], v[64:67]
	s_setprio 0
	s_barrier
	s_add_i32 s8, s13, s11
	v_lshl_add_u64 v[212:213], s[40:41], 0, v[112:113]
	s_mov_b32 m0, s8
	ds_read_b128 v[162:165], v211 offset:16384
	ds_read_b128 v[166:169], v211 offset:17408
	ds_read_b128 v[170:173], v211 offset:18432
	ds_read_b128 v[174:177], v211 offset:19456
	ds_read_b128 v[178:181], v211 offset:20480
	ds_read_b128 v[182:185], v211 offset:21504
	ds_read_b128 v[202:205], v211 offset:22528
	ds_read_b128 v[206:209], v211 offset:23552
	global_load_lds_dwordx4 v112, s[40:41]
	s_add_i32 m0, s8, 0x2000
	s_add_u32 s8, s40, 0x40000
	v_lshl_add_u64 v[214:215], s[40:41], 0, v[200:201]
	s_addc_u32 s9, s41, 0
	s_add_i32 s13, s15, s11
	global_load_lds_dwordx4 v200, s[40:41]
	s_nop 0
	s_mov_b32 m0, s13
	v_lshl_add_u64 v[236:237], s[90:91], 0, v[188:189]
	global_load_lds_dwordx4 v112, s[8:9]
	s_nop 0
	s_add_i32 m0, s13, 0x2000
	s_nop 0
	global_load_lds_dwordx4 v200, s[8:9]
	s_nop 0
	s_mov_b32 m0, s19
	s_nop 0
	global_load_lds_dwordx4 v186, s[90:91]
	s_mov_b32 m0, s23
	s_nop 0
	global_load_lds_dwordx4 v188, s[90:91]
	s_waitcnt vmcnt(8)
	s_waitcnt lgkmcnt(0)
	s_barrier
; #define PG8_STAGE(bufoff, gbase, voff) do { _Pragma("unroll") for (int _i = 0; _i < 2; ++_i) \
;         __builtin_amdgcn_global_load_lds((const unsigned*)((const char*)(gbase) + (voff)[_i]), (LAS unsigned*)(lds + (bufoff) + ldsw + _i * 8192), 16, 0, 0); } while (0)
; #define PG8_LDA(dst, b, h) do { _Pragma("unroll") for (int m = 0; m < 4; ++m) _Pragma("unroll") for (int k = 0; k < 2; ++k) dst[m][k] = *(const LAS bf16x8*)(lds + PG8_SA(b, h) + aoff + m * 2048 + k * 1024); } while (0)
; #define PG8_LDB(dst, b, h) do { _Pragma("unroll") for (int n = 0; n < 2; ++n) _Pragma("unroll") for (int k = 0; k < 2; ++k) dst[n][k] = *(const LAS bf16x8*)(lds + PG8_SB(b, h) + boff + n * 2048 + k * 1024); } while (0)
; #define PG8_MMA(ai, bj, At, Bt) do { __builtin_amdgcn_s_setprio(1); _Pragma("unroll") for (int m = 0; m < 4; ++m) _Pragma("unroll") for (int n = 0; n < 2; ++n) _Pragma("unroll") for (int k = 0; k < 2; ++k) \
;         acc[ai][bj][m][n] = __builtin_amdgcn_mfma_f32_16x16x32_bf16(Bt[n][k], At[m][k], acc[ai][bj][m][n], 0, 0, 0); __builtin_amdgcn_s_setprio(0); } while (0)
; #define PG8_WAIT_V(n) asm volatile("s_waitcnt vmcnt(" #n ")" ::: "memory")
; #define PG8_WAIT_L(n) asm volatile("s_waitcnt lgkmcnt(" #n ")" ::: "memory")
; #define PG8_BAR __builtin_amdgcn_s_barrier()
; #define PG8_SCHED __builtin_amdgcn_sched_barrier(0)
; template <class Epi>
; __device__ __forceinline__ void gemm_phase(LAS unsigned char* lds, const Gemm g, const StaticOrder& S, const Epi& E, const int tid) {
;     ...
;             PG8_WAIT_V(8); PG8_WAIT_L(0); PG8_BAR; PG8_MMA(1, 0, At, B0); PG8_MMA(1, 1, At, B1); PG8_BAR; PG8_SCHED;
;             PG8_LDB(B0, 1, 0); PG8_LDB(B1, 1, 1); PG8_SCHED; PG8_LDA(At, 1, 0); PG8_STAGE(PG8_SA(0, 1), a2 + hstepA, voffA);
;             PG8_WAIT_V(8); PG8_WAIT_L(0); PG8_BAR; PG8_MMA(0, 0, At, B0); PG8_MMA(0, 1, At, B1); PG8_BAR; PG8_SCHED;
	s_setprio 1
	s_waitcnt lgkmcnt(0)
	v_mfma_f32_16x16x32_bf16 v[60:63], v[130:133], v[162:165], v[60:63]
	v_mfma_f32_16x16x32_bf16 v[56:59], v[138:141], v[162:165], v[56:59]
	v_mfma_f32_16x16x32_bf16 v[44:47], v[130:133], v[170:173], v[44:47]
	v_mfma_f32_16x16x32_bf16 v[40:43], v[138:141], v[170:173], v[40:43]
	v_mfma_f32_16x16x32_bf16 v[28:31], v[130:133], v[178:181], v[28:31]
	v_mfma_f32_16x16x32_bf16 v[24:27], v[138:141], v[178:181], v[24:27]
	v_mfma_f32_16x16x32_bf16 v[12:15], v[130:133], v[202:205], v[12:15]
	v_mfma_f32_16x16x32_bf16 v[8:11], v[138:141], v[202:205], v[8:11]
	v_mfma_f32_16x16x32_bf16 v[60:63], v[134:137], v[166:169], v[60:63]
	v_mfma_f32_16x16x32_bf16 v[56:59], v[142:145], v[166:169], v[56:59]
	v_mfma_f32_16x16x32_bf16 v[44:47], v[134:137], v[174:177], v[44:47]
	v_mfma_f32_16x16x32_bf16 v[40:43], v[142:145], v[174:177], v[40:43]
	v_mfma_f32_16x16x32_bf16 v[28:31], v[134:137], v[182:185], v[28:31]
	v_mfma_f32_16x16x32_bf16 v[24:27], v[142:145], v[182:185], v[24:27]
	v_mfma_f32_16x16x32_bf16 v[12:15], v[134:137], v[206:209], v[12:15]
	v_mfma_f32_16x16x32_bf16 v[8:11], v[142:145], v[206:209], v[8:11]
	v_mfma_f32_16x16x32_bf16 v[52:55], v[146:149], v[162:165], v[52:55]
	v_mfma_f32_16x16x32_bf16 v[48:51], v[154:157], v[162:165], v[48:51]
	v_mfma_f32_16x16x32_bf16 v[36:39], v[146:149], v[170:173], v[36:39]
	v_mfma_f32_16x16x32_bf16 v[32:35], v[154:157], v[170:173], v[32:35]
	v_mfma_f32_16x16x32_bf16 v[20:23], v[146:149], v[178:181], v[20:23]
	v_mfma_f32_16x16x32_bf16 v[16:19], v[154:157], v[178:181], v[16:19]
	v_mfma_f32_16x16x32_bf16 v[4:7], v[146:149], v[202:205], v[4:7]
	v_mfma_f32_16x16x32_bf16 v[0:3], v[154:157], v[202:205], v[0:3]
	v_mfma_f32_16x16x32_bf16 v[52:55], v[150:153], v[166:169], v[52:55]
	v_mfma_f32_16x16x32_bf16 v[48:51], v[158:161], v[166:169], v[48:51]
	v_mfma_f32_16x16x32_bf16 v[36:39], v[150:153], v[174:177], v[36:39]
	v_mfma_f32_16x16x32_bf16 v[32:35], v[158:161], v[174:177], v[32:35]
	v_mfma_f32_16x16x32_bf16 v[20:23], v[150:153], v[182:185], v[20:23]
	v_mfma_f32_16x16x32_bf16 v[16:19], v[158:161], v[182:185], v[16:19]
	v_mfma_f32_16x16x32_bf16 v[4:7], v[150:153], v[206:209], v[4:7]
	v_mfma_f32_16x16x32_bf16 v[0:3], v[158:161], v[206:209], v[0:3]
	s_setprio 0
	s_barrier
	s_add_i32 s13, 0, 0x18000
	s_add_i32 s31, 0, 0x1c000
	v_add_u32_e32 v142, s13, v210
	v_add_u32_e32 v158, s31, v210
	ds_read_b128 v[130:133], v142
	ds_read_b128 v[134:137], v142 offset:1024
	ds_read_b128 v[138:141], v142 offset:2048
	ds_read_b128 v[142:145], v142 offset:3072
	ds_read_b128 v[146:149], v158
	ds_read_b128 v[150:153], v158 offset:1024
	ds_read_b128 v[154:157], v158 offset:2048
	ds_read_b128 v[158:161], v158 offset:3072
	s_add_u32 s8, s90, 0x90000
	s_addc_u32 s9, s91, 0
	s_mov_b32 m0, s28
	s_nop 0
	ds_read_b128 v[162:165], v211 offset:32768
	ds_read_b128 v[166:169], v211 offset:33792
	ds_read_b128 v[170:173], v211 offset:34816
	ds_read_b128 v[174:177], v211 offset:35840
	ds_read_b128 v[178:181], v211 offset:36864
	ds_read_b128 v[182:185], v211 offset:37888
	ds_read_b128 v[202:205], v211 offset:38912
	ds_read_b128 v[206:209], v211 offset:39936
	global_load_lds_dwordx4 v186, s[8:9]
	v_lshl_add_u64 v[238:239], s[8:9], 0, v[188:189]
	s_mov_b32 m0, s30
	s_nop 0
	global_load_lds_dwordx4 v188, s[8:9]
	s_waitcnt vmcnt(8)
	s_waitcnt lgkmcnt(0)
	s_barrier
	s_setprio 1
	s_waitcnt lgkmcnt(0)
	v_mfma_f32_16x16x32_bf16 v[126:129], v[130:133], v[162:165], v[126:129]
	v_mfma_f32_16x16x32_bf16 v[122:125], v[138:141], v[162:165], v[122:125]
	v_mfma_f32_16x16x32_bf16 v[108:111], v[130:133], v[170:173], v[108:111]
	v_mfma_f32_16x16x32_bf16 v[104:107], v[138:141], v[170:173], v[104:107]
	v_mfma_f32_16x16x32_bf16 v[92:95], v[130:133], v[178:181], v[92:95]
	v_mfma_f32_16x16x32_bf16 v[88:91], v[138:141], v[178:181], v[88:91]
	v_mfma_f32_16x16x32_bf16 v[76:79], v[130:133], v[202:205], v[76:79]
	v_mfma_f32_16x16x32_bf16 v[72:75], v[138:141], v[202:205], v[72:75]
	v_mfma_f32_16x16x32_bf16 v[126:129], v[134:137], v[166:169], v[126:129]
	v_mfma_f32_16x16x32_bf16 v[122:125], v[142:145], v[166:169], v[122:125]
	v_mfma_f32_16x16x32_bf16 v[108:111], v[134:137], v[174:177], v[108:111]
	v_mfma_f32_16x16x32_bf16 v[104:107], v[142:145], v[174:177], v[104:107]
	v_mfma_f32_16x16x32_bf16 v[92:95], v[134:137], v[182:185], v[92:95]
	v_mfma_f32_16x16x32_bf16 v[88:91], v[142:145], v[182:185], v[88:91]
	v_mfma_f32_16x16x32_bf16 v[76:79], v[134:137], v[206:209], v[76:79]
	v_mfma_f32_16x16x32_bf16 v[72:75], v[142:145], v[206:209], v[72:75]
	v_mfma_f32_16x16x32_bf16 v[118:121], v[146:149], v[162:165], v[118:121]
	v_mfma_f32_16x16x32_bf16 v[114:117], v[154:157], v[162:165], v[114:117]
	v_mfma_f32_16x16x32_bf16 v[100:103], v[146:149], v[170:173], v[100:103]
	v_mfma_f32_16x16x32_bf16 v[96:99], v[154:157], v[170:173], v[96:99]
	v_mfma_f32_16x16x32_bf16 v[84:87], v[146:149], v[178:181], v[84:87]
	v_mfma_f32_16x16x32_bf16 v[80:83], v[154:157], v[178:181], v[80:83]
	v_mfma_f32_16x16x32_bf16 v[68:71], v[146:149], v[202:205], v[68:71]
	v_mfma_f32_16x16x32_bf16 v[64:67], v[154:157], v[202:205], v[64:67]
	v_mfma_f32_16x16x32_bf16 v[118:121], v[150:153], v[166:169], v[118:121]
	v_mfma_f32_16x16x32_bf16 v[114:117], v[158:161], v[166:169], v[114:117]
	v_mfma_f32_16x16x32_bf16 v[100:103], v[150:153], v[174:177], v[100:103]
	v_mfma_f32_16x16x32_bf16 v[96:99], v[158:161], v[174:177], v[96:99]
	v_mfma_f32_16x16x32_bf16 v[84:87], v[150:153], v[182:185], v[84:87]
	v_mfma_f32_16x16x32_bf16 v[80:83], v[158:161], v[182:185], v[80:83]
	v_mfma_f32_16x16x32_bf16 v[68:71], v[150:153], v[206:209], v[68:71]
	v_mfma_f32_16x16x32_bf16 v[64:67], v[158:161], v[206:209], v[64:67]
	s_setprio 0
	s_barrier
; #define PG8_STAGE(bufoff, gbase, voff) do { _Pragma("unroll") for (int _i = 0; _i < 2; ++_i) \
;         __builtin_amdgcn_global_load_lds((const unsigned*)((const char*)(gbase) + (voff)[_i]), (LAS unsigned*)(lds + (bufoff) + ldsw + _i * 8192), 16, 0, 0); } while (0)
; #define PG8_LDA(dst, b, h) do { _Pragma("unroll") for (int m = 0; m < 4; ++m) _Pragma("unroll") for (int k = 0; k < 2; ++k) dst[m][k] = *(const LAS bf16x8*)(lds + PG8_SA(b, h) + aoff + m * 2048 + k * 1024); } while (0)
; #define PG8_MMA(ai, bj, At, Bt) do { __builtin_amdgcn_s_setprio(1); _Pragma("unroll") for (int m = 0; m < 4; ++m) _Pragma("unroll") for (int n = 0; n < 2; ++n) _Pragma("unroll") for (int k = 0; k < 2; ++k) \
;         acc[ai][bj][m][n] = __builtin_amdgcn_mfma_f32_16x16x32_bf16(Bt[n][k], At[m][k], acc[ai][bj][m][n], 0, 0, 0); __builtin_amdgcn_s_setprio(0); } while (0)
; #define PG8_WAIT_V(n) asm volatile("s_waitcnt vmcnt(" #n ")" ::: "memory")
; #define PG8_WAIT_L(n) asm volatile("s_waitcnt lgkmcnt(" #n ")" ::: "memory")
; #define PG8_BAR __builtin_amdgcn_s_barrier()
; #define PG8_SCHED __builtin_amdgcn_sched_barrier(0)
; template <class Epi>
; __device__ __forceinline__ void gemm_phase(LAS unsigned char* lds, const Gemm g, const StaticOrder& S, const Epi& E, const int tid) {
;     ...
;             PG8_LDA(At, 1, 1); PG8_STAGE(PG8_SB(1, 0), b3, voffB); PG8_STAGE(PG8_SB(1, 1), b3 + hstepB, voffB); PG8_STAGE(PG8_SA(1, 0), a3, voffA);
;             PG8_WAIT_V(8); PG8_WAIT_L(0); PG8_BAR; PG8_MMA(1, 0, At, B0); PG8_MMA(1, 1, At, B1); PG8_BAR; PG8_SCHED;
;         }
;         if (wr == 0) PG8_BAR;
	s_add_i32 s8, s13, s11
	s_add_u32 s100, s40, 0x80
	s_addc_u32 s101, s41, 0
	s_mov_b32 m0, s8
	ds_read_b128 v[162:165], v211 offset:49152
	ds_read_b128 v[166:169], v211 offset:50176
	ds_read_b128 v[170:173], v211 offset:51200
	ds_read_b128 v[174:177], v211 offset:52224
	ds_read_b128 v[178:181], v211 offset:53248
	ds_read_b128 v[182:185], v211 offset:54272
	ds_read_b128 v[202:205], v211 offset:55296
	ds_read_b128 v[206:209], v211 offset:56320
	global_load_lds_dwordx4 v112, s[100:101]
	s_add_i32 m0, s8, 0x2000
	s_add_u32 s8, s40, 0x40080
	v_lshl_add_u64 v[212:213], v[214:215], 0, s[24:25]
	s_addc_u32 s9, s41, 0
	s_add_i32 s13, s31, s11
	global_load_lds_dwordx4 v[212:213], off
	s_nop 0
	s_mov_b32 m0, s13
	s_nop 0
	global_load_lds_dwordx4 v112, s[8:9]
	s_nop 0
	s_add_i32 m0, s13, 0x2000
	s_nop 0
	global_load_lds_dwordx4 v200, s[8:9]
	s_add_u32 s100, s90, 0x80
	s_addc_u32 s101, s91, 0
	s_mov_b32 m0, s99
	s_nop 0
	global_load_lds_dwordx4 v186, s[100:101]
	s_add_u32 s100, s90, 0x80
	s_addc_u32 s101, s91, 0
	s_mov_b32 m0, s33
	s_nop 0
	global_load_lds_dwordx4 v188, s[100:101]
	s_waitcnt vmcnt(8)
	s_waitcnt lgkmcnt(0)
	s_barrier
	s_setprio 1
	s_waitcnt lgkmcnt(0)
	v_mfma_f32_16x16x32_bf16 v[60:63], v[130:133], v[162:165], v[60:63]
	v_mfma_f32_16x16x32_bf16 v[56:59], v[138:141], v[162:165], v[56:59]
	v_mfma_f32_16x16x32_bf16 v[44:47], v[130:133], v[170:173], v[44:47]
	v_mfma_f32_16x16x32_bf16 v[40:43], v[138:141], v[170:173], v[40:43]
	v_mfma_f32_16x16x32_bf16 v[28:31], v[130:133], v[178:181], v[28:31]
	v_mfma_f32_16x16x32_bf16 v[24:27], v[138:141], v[178:181], v[24:27]
	v_mfma_f32_16x16x32_bf16 v[12:15], v[130:133], v[202:205], v[12:15]
	v_mfma_f32_16x16x32_bf16 v[8:11], v[138:141], v[202:205], v[8:11]
	v_mfma_f32_16x16x32_bf16 v[60:63], v[134:137], v[166:169], v[60:63]
	v_mfma_f32_16x16x32_bf16 v[56:59], v[142:145], v[166:169], v[56:59]
	v_mfma_f32_16x16x32_bf16 v[44:47], v[134:137], v[174:177], v[44:47]
	v_mfma_f32_16x16x32_bf16 v[40:43], v[142:145], v[174:177], v[40:43]
	v_mfma_f32_16x16x32_bf16 v[28:31], v[134:137], v[182:185], v[28:31]
	v_mfma_f32_16x16x32_bf16 v[24:27], v[142:145], v[182:185], v[24:27]
	v_mfma_f32_16x16x32_bf16 v[12:15], v[134:137], v[206:209], v[12:15]
	v_mfma_f32_16x16x32_bf16 v[8:11], v[142:145], v[206:209], v[8:11]
	v_mfma_f32_16x16x32_bf16 v[52:55], v[146:149], v[162:165], v[52:55]
	v_mfma_f32_16x16x32_bf16 v[48:51], v[154:157], v[162:165], v[48:51]
	v_mfma_f32_16x16x32_bf16 v[36:39], v[146:149], v[170:173], v[36:39]
	v_mfma_f32_16x16x32_bf16 v[32:35], v[154:157], v[170:173], v[32:35]
	v_mfma_f32_16x16x32_bf16 v[20:23], v[146:149], v[178:181], v[20:23]
	v_mfma_f32_16x16x32_bf16 v[16:19], v[154:157], v[178:181], v[16:19]
	v_mfma_f32_16x16x32_bf16 v[4:7], v[146:149], v[202:205], v[4:7]
	v_mfma_f32_16x16x32_bf16 v[0:3], v[154:157], v[202:205], v[0:3]
	v_mfma_f32_16x16x32_bf16 v[52:55], v[150:153], v[166:169], v[52:55]
	v_mfma_f32_16x16x32_bf16 v[48:51], v[158:161], v[166:169], v[48:51]
	v_mfma_f32_16x16x32_bf16 v[36:39], v[150:153], v[174:177], v[36:39]
	v_mfma_f32_16x16x32_bf16 v[32:35], v[158:161], v[174:177], v[32:35]
	v_mfma_f32_16x16x32_bf16 v[20:23], v[150:153], v[182:185], v[20:23]
	v_mfma_f32_16x16x32_bf16 v[16:19], v[158:161], v[182:185], v[16:19]
	v_mfma_f32_16x16x32_bf16 v[4:7], v[150:153], v[206:209], v[4:7]
	v_mfma_f32_16x16x32_bf16 v[0:3], v[158:161], v[206:209], v[0:3]
	s_setprio 0
	s_barrier
	s_add_u32 s88, s88, 0x100
	s_addc_u32 s89, s89, 0
	s_add_u32 vcc_lo, vcc_lo, 0x100
	s_addc_u32 vcc_hi, vcc_hi, 0
	s_cmp_gt_u32 s96, 13
	s_mov_b32 s40, s96
	s_cbranch_scc0 .LBB0_230
	s_and_b64 vcc, exec, s[44:45]
	s_cbranch_vccz .LBB0_233
	s_barrier

; #define PG8_STAGE(bufoff, gbase, voff) do { _Pragma("unroll") for (int _i = 0; _i < 2; ++_i) \
;         __builtin_amdgcn_global_load_lds((const unsigned*)((const char*)(gbase) + (voff)[_i]), (LAS unsigned*)(lds + (bufoff) + ldsw + _i * 8192), 16, 0, 0); } while (0)
; #define PG8_LDA(dst, b, h) do { _Pragma("unroll") for (int m = 0; m < 4; ++m) _Pragma("unroll") for (int k = 0; k < 2; ++k) dst[m][k] = *(const LAS bf16x8*)(lds + PG8_SA(b, h) + aoff + m * 2048 + k * 1024); } while (0)
; #define PG8_LDB(dst, b, h) do { _Pragma("unroll") for (int n = 0; n < 2; ++n) _Pragma("unroll") for (int k = 0; k < 2; ++k) dst[n][k] = *(const LAS bf16x8*)(lds + PG8_SB(b, h) + boff + n * 2048 + k * 1024); } while (0)
; #define PG8_MMA(ai, bj, At, Bt) do { __builtin_amdgcn_s_setprio(1); _Pragma("unroll") for (int m = 0; m < 4; ++m) _Pragma("unroll") for (int n = 0; n < 2; ++n) _Pragma("unroll") for (int k = 0; k < 2; ++k) \
;         acc[ai][bj][m][n] = __builtin_amdgcn_mfma_f32_16x16x32_bf16(Bt[n][k], At[m][k], acc[ai][bj][m][n], 0, 0, 0); __builtin_amdgcn_s_setprio(0); } while (0)
; #define PG8_WAIT_V(n) asm volatile("s_waitcnt vmcnt(" #n ")" ::: "memory")
; #define PG8_WAIT_L(n) asm volatile("s_waitcnt lgkmcnt(" #n ")" ::: "memory")
; #define PG8_BAR __builtin_amdgcn_s_barrier()
; #define PG8_SCHED __builtin_amdgcn_sched_barrier(0)
; template <class Epi>
; __device__ __forceinline__ void gemm_phase(LAS unsigned char* lds, const Gemm g, const StaticOrder& S, const Epi& E, const int tid) {
;     ...
;             const char* a1 = cA + (size_t)(t + 1) * kstep + ((t + 1) >= 8 ? xtra : 0);
;             const char* a2 = last ? nA : cA + (size_t)(t + 2) * kstep + ((t + 2) >= 8 ? xtra : 0); const char* b2 = last ? nB : cB + (size_t)(t + 2) * kstep;
;             const char* a3 = a2 + kstep; const char* b3 = b2 + kstep;
;             PG8_LDB(B0, 0, 0); PG8_LDB(B1, 0, 1); PG8_SCHED; PG8_LDA(At, 0, 0); PG8_STAGE(PG8_SA(1, 1), a1 + hstepA, voffA);
;             PG8_WAIT_V(8); PG8_WAIT_L(0); PG8_BAR; PG8_MMA(0, 0, At, B0); PG8_MMA(0, 1, At, B1); PG8_BAR; PG8_SCHED;
;             PG8_LDA(At, 0, 1); PG8_STAGE(PG8_SB(0, 0), b2, voffB); PG8_STAGE(PG8_SB(0, 1), b2 + hstepB, voffB); PG8_STAGE(PG8_SA(0, 0), a2, voffA);
;             PG8_WAIT_V(8); PG8_WAIT_L(0); PG8_BAR; PG8_MMA(1, 0, At, B0); PG8_MMA(1, 1, At, B1); PG8_BAR; PG8_SCHED;
.LBB0_268:
	s_add_u32 s8, s40, 0xfffc0080
	s_addc_u32 s9, s41, -1
	s_add_i32 s13, 0, 0x10000
	v_add_u32_e32 v162, s13, v167
	ds_read_b128 v[150:153], v162
	ds_read_b128 v[154:157], v162 offset:1024
	ds_read_b128 v[158:161], v162 offset:2048
	ds_read_b128 v[170:173], v162 offset:3072
	v_add_u32_e32 v162, s15, v167
	ds_read_b128 v[174:177], v162
	ds_read_b128 v[178:181], v162 offset:1024
	ds_read_b128 v[182:185], v162 offset:2048
	ds_read_b128 v[186:189], v162 offset:3072
	s_cmp_eq_u32 s85, 12
	s_cselect_b32 vcc_hi, s33, s9
	s_cselect_b32 vcc_lo, s36, s8
	s_cselect_b32 s95, s37, s57
	s_cselect_b32 s94, s45, s46
	s_nop 0
	s_add_i32 m0, s11, 0xc000
	ds_read_b128 v[190:193], v169
	ds_read_b128 v[200:203], v169 offset:1024
	ds_read_b128 v[204:207], v169 offset:2048
	ds_read_b128 v[208:211], v169 offset:3072
	ds_read_b128 v[212:215], v169 offset:4096
	ds_read_b128 v[234:237], v169 offset:5120
	ds_read_b128 v[238:241], v169 offset:6144
	ds_read_b128 v[242:245], v169 offset:7168
	global_load_lds_dwordx4 v146, s[40:41]
	s_nop 0
	s_add_i32 m0, s11, 0xe000
	s_nop 0
	global_load_lds_dwordx4 v148, s[40:41]
	s_waitcnt vmcnt(8)
	s_waitcnt lgkmcnt(0)
	s_barrier
	s_setprio 1
	s_waitcnt lgkmcnt(0)
	v_mfma_f32_16x16x32_bf16 v[134:137], v[150:153], v[190:193], v[134:137]
	v_mfma_f32_16x16x32_bf16 v[130:133], v[158:161], v[190:193], v[130:133]
	v_mfma_f32_16x16x32_bf16 v[118:121], v[150:153], v[204:207], v[118:121]
	v_mfma_f32_16x16x32_bf16 v[114:117], v[158:161], v[204:207], v[114:117]
	v_mfma_f32_16x16x32_bf16 v[100:103], v[150:153], v[212:215], v[100:103]
	v_mfma_f32_16x16x32_bf16 v[96:99], v[158:161], v[212:215], v[96:99]
	v_mfma_f32_16x16x32_bf16 v[84:87], v[150:153], v[238:241], v[84:87]
	v_mfma_f32_16x16x32_bf16 v[80:83], v[158:161], v[238:241], v[80:83]
	v_mfma_f32_16x16x32_bf16 v[134:137], v[154:157], v[200:203], v[134:137]
	v_mfma_f32_16x16x32_bf16 v[130:133], v[170:173], v[200:203], v[130:133]
	v_mfma_f32_16x16x32_bf16 v[118:121], v[154:157], v[208:211], v[118:121]
	v_mfma_f32_16x16x32_bf16 v[114:117], v[170:173], v[208:211], v[114:117]
	v_mfma_f32_16x16x32_bf16 v[100:103], v[154:157], v[234:237], v[100:103]
	v_mfma_f32_16x16x32_bf16 v[96:99], v[170:173], v[234:237], v[96:99]
	v_mfma_f32_16x16x32_bf16 v[84:87], v[154:157], v[242:245], v[84:87]
	v_mfma_f32_16x16x32_bf16 v[80:83], v[170:173], v[242:245], v[80:83]
	v_mfma_f32_16x16x32_bf16 v[126:129], v[174:177], v[190:193], v[126:129]
	v_mfma_f32_16x16x32_bf16 v[122:125], v[182:185], v[190:193], v[122:125]
	v_mfma_f32_16x16x32_bf16 v[108:111], v[174:177], v[204:207], v[108:111]
	v_mfma_f32_16x16x32_bf16 v[104:107], v[182:185], v[204:207], v[104:107]
	v_mfma_f32_16x16x32_bf16 v[92:95], v[174:177], v[212:215], v[92:95]
	v_mfma_f32_16x16x32_bf16 v[88:91], v[182:185], v[212:215], v[88:91]
	v_mfma_f32_16x16x32_bf16 v[76:79], v[174:177], v[238:241], v[76:79]
	v_mfma_f32_16x16x32_bf16 v[72:75], v[182:185], v[238:241], v[72:75]
	v_mfma_f32_16x16x32_bf16 v[126:129], v[178:181], v[200:203], v[126:129]
	v_mfma_f32_16x16x32_bf16 v[122:125], v[186:189], v[200:203], v[122:125]
	v_mfma_f32_16x16x32_bf16 v[108:111], v[178:181], v[208:211], v[108:111]
	v_mfma_f32_16x16x32_bf16 v[104:107], v[186:189], v[208:211], v[104:107]
	v_mfma_f32_16x16x32_bf16 v[92:95], v[178:181], v[234:237], v[92:95]
	v_mfma_f32_16x16x32_bf16 v[88:91], v[186:189], v[234:237], v[88:91]
	v_mfma_f32_16x16x32_bf16 v[76:79], v[178:181], v[242:245], v[76:79]
	v_mfma_f32_16x16x32_bf16 v[72:75], v[186:189], v[242:245], v[72:75]
	s_setprio 0
	s_barrier
	s_add_i32 s8, s13, s81
	s_nop 0
	s_mov_b32 m0, s8
	ds_read_b128 v[190:193], v169 offset:16384
	ds_read_b128 v[200:203], v169 offset:17408
	ds_read_b128 v[204:207], v169 offset:18432
	ds_read_b128 v[208:211], v169 offset:19456
	ds_read_b128 v[212:215], v169 offset:20480
	ds_read_b128 v[234:237], v169 offset:21504
	ds_read_b128 v[238:241], v169 offset:22528
	ds_read_b128 v[242:245], v169 offset:23552
	global_load_lds_dwordx4 v112, s[94:95]
	s_add_i32 m0, s8, 0x2000
	s_add_u32 s8, s94, 0x40000
	v_lshl_add_u64 v[228:229], s[94:95], 0, v[142:143]
	s_addc_u32 s9, s95, 0
	s_add_i32 s13, s15, s81
	global_load_lds_dwordx4 v142, s[94:95]
	s_nop 0
	s_mov_b32 m0, s13
	s_nop 0
	global_load_lds_dwordx4 v112, s[8:9]
	s_nop 0
	s_add_i32 m0, s13, 0x2000
	s_nop 0
	global_load_lds_dwordx4 v142, s[8:9]
	s_nop 0
	s_mov_b32 m0, s11
	s_nop 0
	global_load_lds_dwordx4 v138, vcc
	s_mov_b32 m0, s19
	s_nop 0
	global_load_lds_dwordx4 v140, vcc
	s_waitcnt vmcnt(8)
	s_waitcnt lgkmcnt(0)
	s_barrier
	s_setprio 1
	s_waitcnt lgkmcnt(0)
	v_mfma_f32_16x16x32_bf16 v[68:71], v[150:153], v[190:193], v[68:71]
	v_mfma_f32_16x16x32_bf16 v[64:67], v[158:161], v[190:193], v[64:67]
	v_mfma_f32_16x16x32_bf16 v[52:55], v[150:153], v[204:207], v[52:55]
	v_mfma_f32_16x16x32_bf16 v[48:51], v[158:161], v[204:207], v[48:51]
	v_mfma_f32_16x16x32_bf16 v[36:39], v[150:153], v[212:215], v[36:39]
	v_mfma_f32_16x16x32_bf16 v[32:35], v[158:161], v[212:215], v[32:35]
	v_mfma_f32_16x16x32_bf16 v[20:23], v[150:153], v[238:241], v[20:23]
	v_mfma_f32_16x16x32_bf16 v[16:19], v[158:161], v[238:241], v[16:19]
	v_mfma_f32_16x16x32_bf16 v[68:71], v[154:157], v[200:203], v[68:71]
	v_mfma_f32_16x16x32_bf16 v[64:67], v[170:173], v[200:203], v[64:67]
	v_mfma_f32_16x16x32_bf16 v[52:55], v[154:157], v[208:211], v[52:55]
	v_mfma_f32_16x16x32_bf16 v[48:51], v[170:173], v[208:211], v[48:51]
	v_mfma_f32_16x16x32_bf16 v[36:39], v[154:157], v[234:237], v[36:39]
	v_mfma_f32_16x16x32_bf16 v[32:35], v[170:173], v[234:237], v[32:35]
	v_mfma_f32_16x16x32_bf16 v[20:23], v[154:157], v[242:245], v[20:23]
	v_mfma_f32_16x16x32_bf16 v[16:19], v[170:173], v[242:245], v[16:19]
	v_mfma_f32_16x16x32_bf16 v[60:63], v[174:177], v[190:193], v[60:63]
	v_mfma_f32_16x16x32_bf16 v[56:59], v[182:185], v[190:193], v[56:59]
	v_mfma_f32_16x16x32_bf16 v[44:47], v[174:177], v[204:207], v[44:47]
	v_mfma_f32_16x16x32_bf16 v[40:43], v[182:185], v[204:207], v[40:43]
	v_mfma_f32_16x16x32_bf16 v[28:31], v[174:177], v[212:215], v[28:31]
	v_mfma_f32_16x16x32_bf16 v[24:27], v[182:185], v[212:215], v[24:27]
	v_mfma_f32_16x16x32_bf16 v[12:15], v[174:177], v[238:241], v[12:15]
	v_mfma_f32_16x16x32_bf16 v[8:11], v[182:185], v[238:241], v[8:11]
	v_mfma_f32_16x16x32_bf16 v[60:63], v[178:181], v[200:203], v[60:63]
	v_mfma_f32_16x16x32_bf16 v[56:59], v[186:189], v[200:203], v[56:59]
	v_mfma_f32_16x16x32_bf16 v[44:47], v[178:181], v[208:211], v[44:47]
	v_mfma_f32_16x16x32_bf16 v[40:43], v[186:189], v[208:211], v[40:43]
	v_mfma_f32_16x16x32_bf16 v[28:31], v[178:181], v[234:237], v[28:31]
	v_mfma_f32_16x16x32_bf16 v[24:27], v[186:189], v[234:237], v[24:27]
	v_mfma_f32_16x16x32_bf16 v[12:15], v[178:181], v[242:245], v[12:15]
	v_mfma_f32_16x16x32_bf16 v[8:11], v[186:189], v[242:245], v[8:11]
	s_setprio 0
	s_barrier
; #define PG8_STAGE(bufoff, gbase, voff) do { _Pragma("unroll") for (int _i = 0; _i < 2; ++_i) \
;         __builtin_amdgcn_global_load_lds((const unsigned*)((const char*)(gbase) + (voff)[_i]), (LAS unsigned*)(lds + (bufoff) + ldsw + _i * 8192), 16, 0, 0); } while (0)
; #define PG8_LDA(dst, b, h) do { _Pragma("unroll") for (int m = 0; m < 4; ++m) _Pragma("unroll") for (int k = 0; k < 2; ++k) dst[m][k] = *(const LAS bf16x8*)(lds + PG8_SA(b, h) + aoff + m * 2048 + k * 1024); } while (0)
; #define PG8_LDB(dst, b, h) do { _Pragma("unroll") for (int n = 0; n < 2; ++n) _Pragma("unroll") for (int k = 0; k < 2; ++k) dst[n][k] = *(const LAS bf16x8*)(lds + PG8_SB(b, h) + boff + n * 2048 + k * 1024); } while (0)
; #define PG8_MMA(ai, bj, At, Bt) do { __builtin_amdgcn_s_setprio(1); _Pragma("unroll") for (int m = 0; m < 4; ++m) _Pragma("unroll") for (int n = 0; n < 2; ++n) _Pragma("unroll") for (int k = 0; k < 2; ++k) \
;         acc[ai][bj][m][n] = __builtin_amdgcn_mfma_f32_16x16x32_bf16(Bt[n][k], At[m][k], acc[ai][bj][m][n], 0, 0, 0); __builtin_amdgcn_s_setprio(0); } while (0)
; #define PG8_WAIT_V(n) asm volatile("s_waitcnt vmcnt(" #n ")" ::: "memory")
; #define PG8_WAIT_L(n) asm volatile("s_waitcnt lgkmcnt(" #n ")" ::: "memory")
; #define PG8_BAR __builtin_amdgcn_s_barrier()
; #define PG8_SCHED __builtin_amdgcn_sched_barrier(0)
; template <class Epi>
; __device__ __forceinline__ void gemm_phase(LAS unsigned char* lds, const Gemm g, const StaticOrder& S, const Epi& E, const int tid) {
;     ...
;             PG8_LDB(B0, 1, 0); PG8_LDB(B1, 1, 1); PG8_SCHED; PG8_LDA(At, 1, 0); PG8_STAGE(PG8_SA(0, 1), a2 + hstepA, voffA);
;             PG8_WAIT_V(8); PG8_WAIT_L(0); PG8_BAR; PG8_MMA(0, 0, At, B0); PG8_MMA(0, 1, At, B1); PG8_BAR; PG8_SCHED;
;             PG8_LDA(At, 1, 1); PG8_STAGE(PG8_SB(1, 0), b3, voffB); PG8_STAGE(PG8_SB(1, 1), b3 + hstepB, voffB); PG8_STAGE(PG8_SA(1, 0), a3, voffA);
;             PG8_WAIT_V(8); PG8_WAIT_L(0); PG8_BAR; PG8_MMA(1, 0, At, B0); PG8_MMA(1, 1, At, B1); PG8_BAR; PG8_SCHED;
;         }
;         if (wr == 0) PG8_BAR;
	s_add_i32 s13, 0, 0x18000
	s_add_i32 s31, 0, 0x1c000
	v_add_u32_e32 v170, s13, v167
	v_add_u32_e32 v186, s31, v167
	ds_read_b128 v[150:153], v170
	ds_read_b128 v[154:157], v170 offset:1024
	ds_read_b128 v[158:161], v170 offset:2048
	ds_read_b128 v[170:173], v170 offset:3072
	ds_read_b128 v[174:177], v186
	ds_read_b128 v[178:181], v186 offset:1024
	ds_read_b128 v[182:185], v186 offset:2048
	ds_read_b128 v[186:189], v186 offset:3072
	s_add_u32 s8, vcc_lo, 0x40000
	s_addc_u32 s9, vcc_hi, 0
	s_mov_b32 m0, s98
	s_nop 0
	ds_read_b128 v[190:193], v169 offset:32768
	ds_read_b128 v[200:203], v169 offset:33792
	ds_read_b128 v[204:207], v169 offset:34816
	ds_read_b128 v[208:211], v169 offset:35840
	ds_read_b128 v[212:215], v169 offset:36864
	ds_read_b128 v[234:237], v169 offset:37888
	ds_read_b128 v[238:241], v169 offset:38912
	ds_read_b128 v[242:245], v169 offset:39936
	global_load_lds_dwordx4 v138, s[8:9]
	s_nop 0
	s_mov_b32 m0, s99
	s_nop 0
	global_load_lds_dwordx4 v140, s[8:9]
	s_waitcnt vmcnt(8)
	s_waitcnt lgkmcnt(0)
	s_barrier
	s_setprio 1
	s_waitcnt lgkmcnt(0)
	v_mfma_f32_16x16x32_bf16 v[134:137], v[150:153], v[190:193], v[134:137]
	v_mfma_f32_16x16x32_bf16 v[130:133], v[158:161], v[190:193], v[130:133]
	v_mfma_f32_16x16x32_bf16 v[118:121], v[150:153], v[204:207], v[118:121]
	v_mfma_f32_16x16x32_bf16 v[114:117], v[158:161], v[204:207], v[114:117]
	v_mfma_f32_16x16x32_bf16 v[100:103], v[150:153], v[212:215], v[100:103]
	v_mfma_f32_16x16x32_bf16 v[96:99], v[158:161], v[212:215], v[96:99]
	v_mfma_f32_16x16x32_bf16 v[84:87], v[150:153], v[238:241], v[84:87]
	v_mfma_f32_16x16x32_bf16 v[80:83], v[158:161], v[238:241], v[80:83]
	v_mfma_f32_16x16x32_bf16 v[134:137], v[154:157], v[200:203], v[134:137]
	v_mfma_f32_16x16x32_bf16 v[130:133], v[170:173], v[200:203], v[130:133]
	v_mfma_f32_16x16x32_bf16 v[118:121], v[154:157], v[208:211], v[118:121]
	v_mfma_f32_16x16x32_bf16 v[114:117], v[170:173], v[208:211], v[114:117]
	v_mfma_f32_16x16x32_bf16 v[100:103], v[154:157], v[234:237], v[100:103]
	v_mfma_f32_16x16x32_bf16 v[96:99], v[170:173], v[234:237], v[96:99]
	v_mfma_f32_16x16x32_bf16 v[84:87], v[154:157], v[242:245], v[84:87]
	v_mfma_f32_16x16x32_bf16 v[80:83], v[170:173], v[242:245], v[80:83]
	v_mfma_f32_16x16x32_bf16 v[126:129], v[174:177], v[190:193], v[126:129]
	v_mfma_f32_16x16x32_bf16 v[122:125], v[182:185], v[190:193], v[122:125]
	v_mfma_f32_16x16x32_bf16 v[108:111], v[174:177], v[204:207], v[108:111]
	v_mfma_f32_16x16x32_bf16 v[104:107], v[182:185], v[204:207], v[104:107]
	v_mfma_f32_16x16x32_bf16 v[92:95], v[174:177], v[212:215], v[92:95]
	v_mfma_f32_16x16x32_bf16 v[88:91], v[182:185], v[212:215], v[88:91]
	v_mfma_f32_16x16x32_bf16 v[76:79], v[174:177], v[238:241], v[76:79]
	v_mfma_f32_16x16x32_bf16 v[72:75], v[182:185], v[238:241], v[72:75]
	v_mfma_f32_16x16x32_bf16 v[126:129], v[178:181], v[200:203], v[126:129]
	v_mfma_f32_16x16x32_bf16 v[122:125], v[186:189], v[200:203], v[122:125]
	v_mfma_f32_16x16x32_bf16 v[108:111], v[178:181], v[208:211], v[108:111]
	v_mfma_f32_16x16x32_bf16 v[104:107], v[186:189], v[208:211], v[104:107]
	v_mfma_f32_16x16x32_bf16 v[92:95], v[178:181], v[234:237], v[92:95]
	v_mfma_f32_16x16x32_bf16 v[88:91], v[186:189], v[234:237], v[88:91]
	v_mfma_f32_16x16x32_bf16 v[76:79], v[178:181], v[242:245], v[76:79]
	v_mfma_f32_16x16x32_bf16 v[72:75], v[186:189], v[242:245], v[72:75]
	s_setprio 0
	s_barrier
	s_add_i32 s8, s13, s81
	s_add_u32 s100, s94, 0x80
	s_addc_u32 s101, s95, 0
	s_mov_b32 m0, s8
	ds_read_b128 v[190:193], v169 offset:49152
	ds_read_b128 v[200:203], v169 offset:50176
	ds_read_b128 v[204:207], v169 offset:51200
	ds_read_b128 v[208:211], v169 offset:52224
	ds_read_b128 v[212:215], v169 offset:53248
	ds_read_b128 v[234:237], v169 offset:54272
	ds_read_b128 v[238:241], v169 offset:55296
	ds_read_b128 v[242:245], v169 offset:56320
	global_load_lds_dwordx4 v112, s[100:101]
	s_add_i32 m0, s8, 0x2000
	s_add_u32 s8, s94, 0x40080
	v_lshl_add_u64 v[162:163], v[228:229], 0, s[24:25]
	s_addc_u32 s9, s95, 0
	s_add_i32 s13, s31, s81
	global_load_lds_dwordx4 v[162:163], off
	s_nop 0
	s_mov_b32 m0, s13
	s_nop 0
	global_load_lds_dwordx4 v112, s[8:9]
	s_nop 0
	s_add_i32 m0, s13, 0x2000
	s_nop 0
	global_load_lds_dwordx4 v142, s[8:9]
	s_add_u32 s100, vcc_lo, 0x80
	s_addc_u32 s101, vcc_hi, 0
	s_mov_b32 m0, s38
	s_nop 0
	global_load_lds_dwordx4 v138, s[100:101]
	s_add_u32 s100, vcc_lo, 0x80
	s_addc_u32 s101, vcc_hi, 0
	s_mov_b32 m0, s39
	s_nop 0
	global_load_lds_dwordx4 v140, s[100:101]
	s_waitcnt vmcnt(8)
	s_waitcnt lgkmcnt(0)
	s_barrier
	s_setprio 1
	s_waitcnt lgkmcnt(0)
	v_mfma_f32_16x16x32_bf16 v[68:71], v[150:153], v[190:193], v[68:71]
	v_mfma_f32_16x16x32_bf16 v[64:67], v[158:161], v[190:193], v[64:67]
	v_mfma_f32_16x16x32_bf16 v[52:55], v[150:153], v[204:207], v[52:55]
	v_mfma_f32_16x16x32_bf16 v[48:51], v[158:161], v[204:207], v[48:51]
	v_mfma_f32_16x16x32_bf16 v[36:39], v[150:153], v[212:215], v[36:39]
	v_mfma_f32_16x16x32_bf16 v[32:35], v[158:161], v[212:215], v[32:35]
	v_mfma_f32_16x16x32_bf16 v[20:23], v[150:153], v[238:241], v[20:23]
	v_mfma_f32_16x16x32_bf16 v[16:19], v[158:161], v[238:241], v[16:19]
	v_mfma_f32_16x16x32_bf16 v[68:71], v[154:157], v[200:203], v[68:71]
	v_mfma_f32_16x16x32_bf16 v[64:67], v[170:173], v[200:203], v[64:67]
	v_mfma_f32_16x16x32_bf16 v[52:55], v[154:157], v[208:211], v[52:55]
	v_mfma_f32_16x16x32_bf16 v[48:51], v[170:173], v[208:211], v[48:51]
	v_mfma_f32_16x16x32_bf16 v[36:39], v[154:157], v[234:237], v[36:39]
	v_mfma_f32_16x16x32_bf16 v[32:35], v[170:173], v[234:237], v[32:35]
	v_mfma_f32_16x16x32_bf16 v[20:23], v[154:157], v[242:245], v[20:23]
	v_mfma_f32_16x16x32_bf16 v[16:19], v[170:173], v[242:245], v[16:19]
	v_mfma_f32_16x16x32_bf16 v[60:63], v[174:177], v[190:193], v[60:63]
	v_mfma_f32_16x16x32_bf16 v[56:59], v[182:185], v[190:193], v[56:59]
	v_mfma_f32_16x16x32_bf16 v[44:47], v[174:177], v[204:207], v[44:47]
	v_mfma_f32_16x16x32_bf16 v[40:43], v[182:185], v[204:207], v[40:43]
	v_mfma_f32_16x16x32_bf16 v[28:31], v[174:177], v[212:215], v[28:31]
	v_mfma_f32_16x16x32_bf16 v[24:27], v[182:185], v[212:215], v[24:27]
	v_mfma_f32_16x16x32_bf16 v[12:15], v[174:177], v[238:241], v[12:15]
	v_mfma_f32_16x16x32_bf16 v[8:11], v[182:185], v[238:241], v[8:11]
	v_mfma_f32_16x16x32_bf16 v[60:63], v[178:181], v[200:203], v[60:63]
	v_mfma_f32_16x16x32_bf16 v[56:59], v[186:189], v[200:203], v[56:59]
	v_mfma_f32_16x16x32_bf16 v[44:47], v[178:181], v[208:211], v[44:47]
	v_mfma_f32_16x16x32_bf16 v[40:43], v[186:189], v[208:211], v[40:43]
	v_mfma_f32_16x16x32_bf16 v[28:31], v[178:181], v[234:237], v[28:31]
	v_mfma_f32_16x16x32_bf16 v[24:27], v[186:189], v[234:237], v[24:27]
	v_mfma_f32_16x16x32_bf16 v[12:15], v[178:181], v[242:245], v[12:15]
	v_mfma_f32_16x16x32_bf16 v[8:11], v[186:189], v[242:245], v[8:11]
	s_setprio 0
	s_barrier
	s_add_i32 s85, s85, 2
	s_add_u32 s40, s40, 0x100
	s_addc_u32 s41, s41, 0
	s_add_u32 s46, s46, 0x100
	s_addc_u32 s57, s57, 0
	s_cmp_gt_u32 s85, 13
	s_cbranch_scc0 .LBB0_268
	s_and_b64 vcc, exec, s[82:83]
	s_cbranch_vccz .LBB0_271
	s_barrier

; #define PG8_STAGE(bufoff, gbase, voff) do { _Pragma("unroll") for (int _i = 0; _i < 2; ++_i) \
;         __builtin_amdgcn_global_load_lds((const unsigned*)((const char*)(gbase) + (voff)[_i]), (LAS unsigned*)(lds + (bufoff) + ldsw + _i * 8192), 16, 0, 0); } while (0)
; #define PG8_LDA(dst, b, h) do { _Pragma("unroll") for (int m = 0; m < 4; ++m) _Pragma("unroll") for (int k = 0; k < 2; ++k) dst[m][k] = *(const LAS bf16x8*)(lds + PG8_SA(b, h) + aoff + m * 2048 + k * 1024); } while (0)
; #define PG8_LDB(dst, b, h) do { _Pragma("unroll") for (int n = 0; n < 2; ++n) _Pragma("unroll") for (int k = 0; k < 2; ++k) dst[n][k] = *(const LAS bf16x8*)(lds + PG8_SB(b, h) + boff + n * 2048 + k * 1024); } while (0)
; #define PG8_MMA(ai, bj, At, Bt) do { __builtin_amdgcn_s_setprio(1); _Pragma("unroll") for (int m = 0; m < 4; ++m) _Pragma("unroll") for (int n = 0; n < 2; ++n) _Pragma("unroll") for (int k = 0; k < 2; ++k) \
;         acc[ai][bj][m][n] = __builtin_amdgcn_mfma_f32_16x16x32_bf16(Bt[n][k], At[m][k], acc[ai][bj][m][n], 0, 0, 0); __builtin_amdgcn_s_setprio(0); } while (0)
; #define PG8_WAIT_V(n) asm volatile("s_waitcnt vmcnt(" #n ")" ::: "memory")
; #define PG8_WAIT_L(n) asm volatile("s_waitcnt lgkmcnt(" #n ")" ::: "memory")
; #define PG8_BAR __builtin_amdgcn_s_barrier()
; #define PG8_SCHED __builtin_amdgcn_sched_barrier(0)
; template <class Epi>
; __device__ __forceinline__ void gemm_phase(LAS unsigned char* lds, const Gemm g, const StaticOrder& S, const Epi& E, const int tid) {
;     ...
;             const char* a1 = cA + (size_t)(t + 1) * kstep + ((t + 1) >= 8 ? xtra : 0);
;             const char* a2 = last ? nA : cA + (size_t)(t + 2) * kstep + ((t + 2) >= 8 ? xtra : 0); const char* b2 = last ? nB : cB + (size_t)(t + 2) * kstep;
;             const char* a3 = a2 + kstep; const char* b3 = b2 + kstep;
;             PG8_LDB(B0, 0, 0); PG8_LDB(B1, 0, 1); PG8_SCHED; PG8_LDA(At, 0, 0); PG8_STAGE(PG8_SA(1, 1), a1 + hstepA, voffA);
;             PG8_WAIT_V(8); PG8_WAIT_L(0); PG8_BAR; PG8_MMA(0, 0, At, B0); PG8_MMA(0, 1, At, B1); PG8_BAR; PG8_SCHED;
;             PG8_LDA(At, 0, 1); PG8_STAGE(PG8_SB(0, 0), b2, voffB); PG8_STAGE(PG8_SB(0, 1), b2 + hstepB, voffB); PG8_STAGE(PG8_SA(0, 0), a2, voffA);
;             PG8_WAIT_V(8); PG8_WAIT_L(0); PG8_BAR; PG8_MMA(1, 0, At, B0); PG8_MMA(1, 1, At, B1); PG8_BAR; PG8_SCHED;
.LBB0_356:
	s_add_u32 s8, s42, 0xfffc0080
	s_addc_u32 s9, s43, -1
	s_add_i32 s13, 0, 0x10000
	v_add_u32_e32 v168, s13, v161
	v_add_u32_e32 v184, s15, v161
	ds_read_b128 v[150:153], v168
	ds_read_b128 v[154:157], v168 offset:1024
	ds_read_b128 v[164:167], v168 offset:2048
	ds_read_b128 v[168:171], v168 offset:3072
	ds_read_b128 v[172:175], v184
	ds_read_b128 v[176:179], v184 offset:1024
	ds_read_b128 v[180:183], v184 offset:2048
	ds_read_b128 v[184:187], v184 offset:3072
	s_cmp_eq_u32 s97, 12
	s_cselect_b32 s95, s98, s9
	s_cselect_b32 s94, s99, s8
	s_cselect_b32 s93, s83, s96
	s_cselect_b32 s92, vcc_lo, vcc_hi
	s_nop 0
	s_add_i32 m0, s19, 0xc000
	ds_read_b128 v[188:191], v163
	ds_read_b128 v[200:203], v163 offset:1024
	ds_read_b128 v[204:207], v163 offset:2048
	ds_read_b128 v[208:211], v163 offset:3072
	ds_read_b128 v[212:215], v163 offset:4096
	ds_read_b128 v[234:237], v163 offset:5120
	ds_read_b128 v[238:241], v163 offset:6144
	ds_read_b128 v[242:245], v163 offset:7168
	global_load_lds_dwordx4 v146, s[42:43]
	s_nop 0
	s_add_i32 m0, s19, 0xe000
	s_nop 0
	global_load_lds_dwordx4 v148, s[42:43]
	s_waitcnt vmcnt(8)
	s_waitcnt lgkmcnt(0)
	s_barrier
	s_setprio 1
	s_waitcnt lgkmcnt(0)
	v_mfma_f32_16x16x32_bf16 v[134:137], v[150:153], v[188:191], v[134:137]
	v_mfma_f32_16x16x32_bf16 v[130:133], v[164:167], v[188:191], v[130:133]
	v_mfma_f32_16x16x32_bf16 v[122:125], v[150:153], v[204:207], v[122:125]
	v_mfma_f32_16x16x32_bf16 v[114:117], v[164:167], v[204:207], v[114:117]
	v_mfma_f32_16x16x32_bf16 v[104:107], v[150:153], v[212:215], v[104:107]
	v_mfma_f32_16x16x32_bf16 v[96:99], v[164:167], v[212:215], v[96:99]
	v_mfma_f32_16x16x32_bf16 v[88:91], v[150:153], v[238:241], v[88:91]
	v_mfma_f32_16x16x32_bf16 v[80:83], v[164:167], v[238:241], v[80:83]
	v_mfma_f32_16x16x32_bf16 v[134:137], v[154:157], v[200:203], v[134:137]
	v_mfma_f32_16x16x32_bf16 v[130:133], v[168:171], v[200:203], v[130:133]
	v_mfma_f32_16x16x32_bf16 v[122:125], v[154:157], v[208:211], v[122:125]
	v_mfma_f32_16x16x32_bf16 v[114:117], v[168:171], v[208:211], v[114:117]
	v_mfma_f32_16x16x32_bf16 v[104:107], v[154:157], v[234:237], v[104:107]
	v_mfma_f32_16x16x32_bf16 v[96:99], v[168:171], v[234:237], v[96:99]
	v_mfma_f32_16x16x32_bf16 v[88:91], v[154:157], v[242:245], v[88:91]
	v_mfma_f32_16x16x32_bf16 v[80:83], v[168:171], v[242:245], v[80:83]
	v_mfma_f32_16x16x32_bf16 v[126:129], v[172:175], v[188:191], v[126:129]
	v_mfma_f32_16x16x32_bf16 v[118:121], v[180:183], v[188:191], v[118:121]
	v_mfma_f32_16x16x32_bf16 v[108:111], v[172:175], v[204:207], v[108:111]
	v_mfma_f32_16x16x32_bf16 v[100:103], v[180:183], v[204:207], v[100:103]
	v_mfma_f32_16x16x32_bf16 v[92:95], v[172:175], v[212:215], v[92:95]
	v_mfma_f32_16x16x32_bf16 v[84:87], v[180:183], v[212:215], v[84:87]
	v_mfma_f32_16x16x32_bf16 v[76:79], v[172:175], v[238:241], v[76:79]
	v_mfma_f32_16x16x32_bf16 v[72:75], v[180:183], v[238:241], v[72:75]
	v_mfma_f32_16x16x32_bf16 v[126:129], v[176:179], v[200:203], v[126:129]
	v_mfma_f32_16x16x32_bf16 v[118:121], v[184:187], v[200:203], v[118:121]
	v_mfma_f32_16x16x32_bf16 v[108:111], v[176:179], v[208:211], v[108:111]
	v_mfma_f32_16x16x32_bf16 v[100:103], v[184:187], v[208:211], v[100:103]
	v_mfma_f32_16x16x32_bf16 v[92:95], v[176:179], v[234:237], v[92:95]
	v_mfma_f32_16x16x32_bf16 v[84:87], v[184:187], v[234:237], v[84:87]
	v_mfma_f32_16x16x32_bf16 v[76:79], v[176:179], v[242:245], v[76:79]
	v_mfma_f32_16x16x32_bf16 v[72:75], v[184:187], v[242:245], v[72:75]
	s_setprio 0
	s_barrier
	s_add_i32 s8, s13, s17
	s_nop 0
	s_mov_b32 m0, s8
	ds_read_b128 v[188:191], v163 offset:16384
	ds_read_b128 v[200:203], v163 offset:17408
	ds_read_b128 v[204:207], v163 offset:18432
	ds_read_b128 v[208:211], v163 offset:19456
	ds_read_b128 v[212:215], v163 offset:20480
	ds_read_b128 v[234:237], v163 offset:21504
	ds_read_b128 v[238:241], v163 offset:22528
	ds_read_b128 v[242:245], v163 offset:23552
	global_load_lds_dwordx4 v112, s[92:93]
	s_add_i32 m0, s8, 0x2000
	s_add_u32 s8, s92, 0x40000
	v_lshl_add_u64 v[246:247], s[92:93], 0, v[142:143]
	s_addc_u32 s9, s93, 0
	s_add_i32 s13, s15, s17
	global_load_lds_dwordx4 v142, s[92:93]
	s_nop 0
	s_mov_b32 m0, s13
	s_nop 0
	global_load_lds_dwordx4 v112, s[8:9]
	s_nop 0
	s_add_i32 m0, s13, 0x2000
	s_nop 0
	global_load_lds_dwordx4 v142, s[8:9]
	s_nop 0
	s_mov_b32 m0, s19
	s_nop 0
	global_load_lds_dwordx4 v138, s[94:95]
	s_mov_b32 m0, s23
	s_nop 0
	global_load_lds_dwordx4 v140, s[94:95]
	s_waitcnt vmcnt(8)
	s_waitcnt lgkmcnt(0)
	s_barrier
	s_setprio 1
	s_waitcnt lgkmcnt(0)
	v_mfma_f32_16x16x32_bf16 v[68:71], v[150:153], v[188:191], v[68:71]
	v_mfma_f32_16x16x32_bf16 v[64:67], v[164:167], v[188:191], v[64:67]
	v_mfma_f32_16x16x32_bf16 v[56:59], v[150:153], v[204:207], v[56:59]
	v_mfma_f32_16x16x32_bf16 v[48:51], v[164:167], v[204:207], v[48:51]
	v_mfma_f32_16x16x32_bf16 v[40:43], v[150:153], v[212:215], v[40:43]
	v_mfma_f32_16x16x32_bf16 v[32:35], v[164:167], v[212:215], v[32:35]
	v_mfma_f32_16x16x32_bf16 v[24:27], v[150:153], v[238:241], v[24:27]
	v_mfma_f32_16x16x32_bf16 v[16:19], v[164:167], v[238:241], v[16:19]
	v_mfma_f32_16x16x32_bf16 v[68:71], v[154:157], v[200:203], v[68:71]
	v_mfma_f32_16x16x32_bf16 v[64:67], v[168:171], v[200:203], v[64:67]
	v_mfma_f32_16x16x32_bf16 v[56:59], v[154:157], v[208:211], v[56:59]
	v_mfma_f32_16x16x32_bf16 v[48:51], v[168:171], v[208:211], v[48:51]
	v_mfma_f32_16x16x32_bf16 v[40:43], v[154:157], v[234:237], v[40:43]
	v_mfma_f32_16x16x32_bf16 v[32:35], v[168:171], v[234:237], v[32:35]
	v_mfma_f32_16x16x32_bf16 v[24:27], v[154:157], v[242:245], v[24:27]
	v_mfma_f32_16x16x32_bf16 v[16:19], v[168:171], v[242:245], v[16:19]
	v_mfma_f32_16x16x32_bf16 v[60:63], v[172:175], v[188:191], v[60:63]
	v_mfma_f32_16x16x32_bf16 v[52:55], v[180:183], v[188:191], v[52:55]
	v_mfma_f32_16x16x32_bf16 v[44:47], v[172:175], v[204:207], v[44:47]
	v_mfma_f32_16x16x32_bf16 v[36:39], v[180:183], v[204:207], v[36:39]
	v_mfma_f32_16x16x32_bf16 v[28:31], v[172:175], v[212:215], v[28:31]
	v_mfma_f32_16x16x32_bf16 v[20:23], v[180:183], v[212:215], v[20:23]
	v_mfma_f32_16x16x32_bf16 v[12:15], v[172:175], v[238:241], v[12:15]
	v_mfma_f32_16x16x32_bf16 v[8:11], v[180:183], v[238:241], v[8:11]
	v_mfma_f32_16x16x32_bf16 v[60:63], v[176:179], v[200:203], v[60:63]
	v_mfma_f32_16x16x32_bf16 v[52:55], v[184:187], v[200:203], v[52:55]
	v_mfma_f32_16x16x32_bf16 v[44:47], v[176:179], v[208:211], v[44:47]
	v_mfma_f32_16x16x32_bf16 v[36:39], v[184:187], v[208:211], v[36:39]
	v_mfma_f32_16x16x32_bf16 v[28:31], v[176:179], v[234:237], v[28:31]
	v_mfma_f32_16x16x32_bf16 v[20:23], v[184:187], v[234:237], v[20:23]
	v_mfma_f32_16x16x32_bf16 v[12:15], v[176:179], v[242:245], v[12:15]
	v_mfma_f32_16x16x32_bf16 v[8:11], v[184:187], v[242:245], v[8:11]
	s_setprio 0
	s_barrier
; #define PG8_STAGE(bufoff, gbase, voff) do { _Pragma("unroll") for (int _i = 0; _i < 2; ++_i) \
;         __builtin_amdgcn_global_load_lds((const unsigned*)((const char*)(gbase) + (voff)[_i]), (LAS unsigned*)(lds + (bufoff) + ldsw + _i * 8192), 16, 0, 0); } while (0)
; #define PG8_LDA(dst, b, h) do { _Pragma("unroll") for (int m = 0; m < 4; ++m) _Pragma("unroll") for (int k = 0; k < 2; ++k) dst[m][k] = *(const LAS bf16x8*)(lds + PG8_SA(b, h) + aoff + m * 2048 + k * 1024); } while (0)
; #define PG8_LDB(dst, b, h) do { _Pragma("unroll") for (int n = 0; n < 2; ++n) _Pragma("unroll") for (int k = 0; k < 2; ++k) dst[n][k] = *(const LAS bf16x8*)(lds + PG8_SB(b, h) + boff + n * 2048 + k * 1024); } while (0)
; #define PG8_MMA(ai, bj, At, Bt) do { __builtin_amdgcn_s_setprio(1); _Pragma("unroll") for (int m = 0; m < 4; ++m) _Pragma("unroll") for (int n = 0; n < 2; ++n) _Pragma("unroll") for (int k = 0; k < 2; ++k) \
;         acc[ai][bj][m][n] = __builtin_amdgcn_mfma_f32_16x16x32_bf16(Bt[n][k], At[m][k], acc[ai][bj][m][n], 0, 0, 0); __builtin_amdgcn_s_setprio(0); } while (0)
; #define PG8_WAIT_V(n) asm volatile("s_waitcnt vmcnt(" #n ")" ::: "memory")
; #define PG8_WAIT_L(n) asm volatile("s_waitcnt lgkmcnt(" #n ")" ::: "memory")
; #define PG8_BAR __builtin_amdgcn_s_barrier()
; #define PG8_SCHED __builtin_amdgcn_sched_barrier(0)
; template <class Epi>
; __device__ __forceinline__ void gemm_phase(LAS unsigned char* lds, const Gemm g, const StaticOrder& S, const Epi& E, const int tid) {
;     ...
;             PG8_LDB(B0, 1, 0); PG8_LDB(B1, 1, 1); PG8_SCHED; PG8_LDA(At, 1, 0); PG8_STAGE(PG8_SA(0, 1), a2 + hstepA, voffA);
;             PG8_WAIT_V(8); PG8_WAIT_L(0); PG8_BAR; PG8_MMA(0, 0, At, B0); PG8_MMA(0, 1, At, B1); PG8_BAR; PG8_SCHED;
;             PG8_LDA(At, 1, 1); PG8_STAGE(PG8_SB(1, 0), b3, voffB); PG8_STAGE(PG8_SB(1, 1), b3 + hstepB, voffB); PG8_STAGE(PG8_SA(1, 0), a3, voffA);
;             PG8_WAIT_V(8); PG8_WAIT_L(0); PG8_BAR; PG8_MMA(1, 0, At, B0); PG8_MMA(1, 1, At, B1); PG8_BAR; PG8_SCHED;
;         }
;         if (wr == 0) PG8_BAR;
	s_add_i32 s13, 0, 0x18000
	s_add_i32 s31, 0, 0x1c000
	v_add_u32_e32 v168, s13, v161
	v_add_u32_e32 v184, s31, v161
	ds_read_b128 v[150:153], v168
	ds_read_b128 v[154:157], v168 offset:1024
	ds_read_b128 v[164:167], v168 offset:2048
	ds_read_b128 v[168:171], v168 offset:3072
	ds_read_b128 v[172:175], v184
	ds_read_b128 v[176:179], v184 offset:1024
	ds_read_b128 v[180:183], v184 offset:2048
	ds_read_b128 v[184:187], v184 offset:3072
	s_add_u32 s8, s94, 0x40000
	s_addc_u32 s9, s95, 0
	s_mov_b32 m0, s28
	s_nop 0
	ds_read_b128 v[188:191], v163 offset:32768
	ds_read_b128 v[200:203], v163 offset:33792
	ds_read_b128 v[204:207], v163 offset:34816
	ds_read_b128 v[208:211], v163 offset:35840
	ds_read_b128 v[212:215], v163 offset:36864
	ds_read_b128 v[234:237], v163 offset:37888
	ds_read_b128 v[238:241], v163 offset:38912
	ds_read_b128 v[242:245], v163 offset:39936
	global_load_lds_dwordx4 v138, s[8:9]
	s_nop 0
	s_mov_b32 m0, s30
	s_nop 0
	global_load_lds_dwordx4 v140, s[8:9]
	s_waitcnt vmcnt(8)
	s_waitcnt lgkmcnt(0)
	s_barrier
	s_setprio 1
	s_waitcnt lgkmcnt(0)
	v_mfma_f32_16x16x32_bf16 v[134:137], v[150:153], v[188:191], v[134:137]
	v_mfma_f32_16x16x32_bf16 v[130:133], v[164:167], v[188:191], v[130:133]
	v_mfma_f32_16x16x32_bf16 v[122:125], v[150:153], v[204:207], v[122:125]
	v_mfma_f32_16x16x32_bf16 v[114:117], v[164:167], v[204:207], v[114:117]
	v_mfma_f32_16x16x32_bf16 v[104:107], v[150:153], v[212:215], v[104:107]
	v_mfma_f32_16x16x32_bf16 v[96:99], v[164:167], v[212:215], v[96:99]
	v_mfma_f32_16x16x32_bf16 v[88:91], v[150:153], v[238:241], v[88:91]
	v_mfma_f32_16x16x32_bf16 v[80:83], v[164:167], v[238:241], v[80:83]
	v_mfma_f32_16x16x32_bf16 v[134:137], v[154:157], v[200:203], v[134:137]
	v_mfma_f32_16x16x32_bf16 v[130:133], v[168:171], v[200:203], v[130:133]
	v_mfma_f32_16x16x32_bf16 v[122:125], v[154:157], v[208:211], v[122:125]
	v_mfma_f32_16x16x32_bf16 v[114:117], v[168:171], v[208:211], v[114:117]
	v_mfma_f32_16x16x32_bf16 v[104:107], v[154:157], v[234:237], v[104:107]
	v_mfma_f32_16x16x32_bf16 v[96:99], v[168:171], v[234:237], v[96:99]
	v_mfma_f32_16x16x32_bf16 v[88:91], v[154:157], v[242:245], v[88:91]
	v_mfma_f32_16x16x32_bf16 v[80:83], v[168:171], v[242:245], v[80:83]
	v_mfma_f32_16x16x32_bf16 v[126:129], v[172:175], v[188:191], v[126:129]
	v_mfma_f32_16x16x32_bf16 v[118:121], v[180:183], v[188:191], v[118:121]
	v_mfma_f32_16x16x32_bf16 v[108:111], v[172:175], v[204:207], v[108:111]
	v_mfma_f32_16x16x32_bf16 v[100:103], v[180:183], v[204:207], v[100:103]
	v_mfma_f32_16x16x32_bf16 v[92:95], v[172:175], v[212:215], v[92:95]
	v_mfma_f32_16x16x32_bf16 v[84:87], v[180:183], v[212:215], v[84:87]
	v_mfma_f32_16x16x32_bf16 v[76:79], v[172:175], v[238:241], v[76:79]
	v_mfma_f32_16x16x32_bf16 v[72:75], v[180:183], v[238:241], v[72:75]
	v_mfma_f32_16x16x32_bf16 v[126:129], v[176:179], v[200:203], v[126:129]
	v_mfma_f32_16x16x32_bf16 v[118:121], v[184:187], v[200:203], v[118:121]
	v_mfma_f32_16x16x32_bf16 v[108:111], v[176:179], v[208:211], v[108:111]
	v_mfma_f32_16x16x32_bf16 v[100:103], v[184:187], v[208:211], v[100:103]
	v_mfma_f32_16x16x32_bf16 v[92:95], v[176:179], v[234:237], v[92:95]
	v_mfma_f32_16x16x32_bf16 v[84:87], v[184:187], v[234:237], v[84:87]
	v_mfma_f32_16x16x32_bf16 v[76:79], v[176:179], v[242:245], v[76:79]
	v_mfma_f32_16x16x32_bf16 v[72:75], v[184:187], v[242:245], v[72:75]
	s_setprio 0
	s_barrier
	s_add_i32 s8, s13, s17
	s_add_u32 s100, s92, 0x80
	s_addc_u32 s101, s93, 0
	s_mov_b32 m0, s8
	ds_read_b128 v[188:191], v163 offset:49152
	ds_read_b128 v[200:203], v163 offset:50176
	ds_read_b128 v[204:207], v163 offset:51200
	ds_read_b128 v[208:211], v163 offset:52224
	ds_read_b128 v[212:215], v163 offset:53248
	ds_read_b128 v[234:237], v163 offset:54272
	ds_read_b128 v[238:241], v163 offset:55296
	ds_read_b128 v[242:245], v163 offset:56320
	global_load_lds_dwordx4 v112, s[100:101]
	s_add_i32 m0, s8, 0x2000
	s_add_u32 s8, s92, 0x40080
	v_lshl_add_u64 v[192:193], v[246:247], 0, s[24:25]
	s_addc_u32 s9, s93, 0
	s_add_i32 s13, s31, s17
	global_load_lds_dwordx4 v[192:193], off
	s_nop 0
	s_mov_b32 m0, s13
	s_nop 0
	global_load_lds_dwordx4 v112, s[8:9]
	s_nop 0
	s_add_i32 m0, s13, 0x2000
	s_nop 0
	global_load_lds_dwordx4 v142, s[8:9]
	s_add_u32 s100, s94, 0x80
	s_addc_u32 s101, s95, 0
	s_mov_b32 m0, s36
	s_nop 0
	global_load_lds_dwordx4 v138, s[100:101]
	s_add_u32 s100, s94, 0x80
	s_addc_u32 s101, s95, 0
	s_mov_b32 m0, s37
	s_nop 0
	global_load_lds_dwordx4 v140, s[100:101]
	s_waitcnt vmcnt(8)
	s_waitcnt lgkmcnt(0)
	s_barrier
	s_setprio 1
	s_waitcnt lgkmcnt(0)
	v_mfma_f32_16x16x32_bf16 v[68:71], v[150:153], v[188:191], v[68:71]
	v_mfma_f32_16x16x32_bf16 v[64:67], v[164:167], v[188:191], v[64:67]
	v_mfma_f32_16x16x32_bf16 v[56:59], v[150:153], v[204:207], v[56:59]
	v_mfma_f32_16x16x32_bf16 v[48:51], v[164:167], v[204:207], v[48:51]
	v_mfma_f32_16x16x32_bf16 v[40:43], v[150:153], v[212:215], v[40:43]
	v_mfma_f32_16x16x32_bf16 v[32:35], v[164:167], v[212:215], v[32:35]
	v_mfma_f32_16x16x32_bf16 v[24:27], v[150:153], v[238:241], v[24:27]
	v_mfma_f32_16x16x32_bf16 v[16:19], v[164:167], v[238:241], v[16:19]
	v_mfma_f32_16x16x32_bf16 v[68:71], v[154:157], v[200:203], v[68:71]
	v_mfma_f32_16x16x32_bf16 v[64:67], v[168:171], v[200:203], v[64:67]
	v_mfma_f32_16x16x32_bf16 v[56:59], v[154:157], v[208:211], v[56:59]
	v_mfma_f32_16x16x32_bf16 v[48:51], v[168:171], v[208:211], v[48:51]
	v_mfma_f32_16x16x32_bf16 v[40:43], v[154:157], v[234:237], v[40:43]
	v_mfma_f32_16x16x32_bf16 v[32:35], v[168:171], v[234:237], v[32:35]
	v_mfma_f32_16x16x32_bf16 v[24:27], v[154:157], v[242:245], v[24:27]
	v_mfma_f32_16x16x32_bf16 v[16:19], v[168:171], v[242:245], v[16:19]
	v_mfma_f32_16x16x32_bf16 v[60:63], v[172:175], v[188:191], v[60:63]
	v_mfma_f32_16x16x32_bf16 v[52:55], v[180:183], v[188:191], v[52:55]
	v_mfma_f32_16x16x32_bf16 v[44:47], v[172:175], v[204:207], v[44:47]
	v_mfma_f32_16x16x32_bf16 v[36:39], v[180:183], v[204:207], v[36:39]
	v_mfma_f32_16x16x32_bf16 v[28:31], v[172:175], v[212:215], v[28:31]
	v_mfma_f32_16x16x32_bf16 v[20:23], v[180:183], v[212:215], v[20:23]
	v_mfma_f32_16x16x32_bf16 v[12:15], v[172:175], v[238:241], v[12:15]
	v_mfma_f32_16x16x32_bf16 v[8:11], v[180:183], v[238:241], v[8:11]
	v_mfma_f32_16x16x32_bf16 v[60:63], v[176:179], v[200:203], v[60:63]
	v_mfma_f32_16x16x32_bf16 v[52:55], v[184:187], v[200:203], v[52:55]
	v_mfma_f32_16x16x32_bf16 v[44:47], v[176:179], v[208:211], v[44:47]
	v_mfma_f32_16x16x32_bf16 v[36:39], v[184:187], v[208:211], v[36:39]
	v_mfma_f32_16x16x32_bf16 v[28:31], v[176:179], v[234:237], v[28:31]
	v_mfma_f32_16x16x32_bf16 v[20:23], v[184:187], v[234:237], v[20:23]
	v_mfma_f32_16x16x32_bf16 v[12:15], v[176:179], v[242:245], v[12:15]
	v_mfma_f32_16x16x32_bf16 v[8:11], v[184:187], v[242:245], v[8:11]
	s_setprio 0
	s_barrier
	s_add_i32 s97, s97, 2
	s_add_u32 s42, s42, 0x100
	s_addc_u32 s43, s43, 0
	s_add_u32 vcc_hi, vcc_hi, 0x100
	s_addc_u32 s96, s96, 0
	s_cmp_gt_u32 s97, 13
	s_cbranch_scc0 .LBB0_356
	s_and_b64 vcc, exec, s[80:81]
	s_cbranch_vccz .LBB0_359
	s_barrier
